# K-loop: s_setprio 1 moved before the start-of-MMA barrier, redundant lgkmcnt(0) after it removed, end-of-MMA barrier issued before s_setprio 0
# baseline (speedup 1.0000x reference)
; template <class Epi, class Sched, bool ALIGN_EPI = false, bool SP2 = false>
; __device__ __forceinline__ void gemm_phase(PG8_LAS unsigned char* lds, const Gemm g, const Sched& S, const Epi& E) {
;     ...
;         const bool has_next = S.next(ui + 1, nxt);
;         const char* nA = has_next ? (const char*)g.A + (size_t)nxt.pm * tstepA : cA; const char* nB = has_next ? (const char*)g.Bt + (size_t)nxt.pn * tstepB : cB;
.LBB0_160:
	s_ashr_i32 s55, s54, 31
	s_lshl_b64 s[2:3], s[54:55], 15
	v_readlane_b32 s8, v255, 15
	s_add_u32 s12, s8, s2
	v_readlane_b32 s2, v255, 16
	s_addc_u32 s13, s2, s3
	s_ashr_i32 s49, s48, 31
	s_lshl_b64 s[2:3], s[48:49], 19
	v_readlane_b32 s8, v255, 29
	s_add_u32 s46, s8, s2
	v_readlane_b32 s2, v255, 40
	s_addc_u32 s47, s2, s3
	s_add_u32 s28, s24, 0x800000
	s_addc_u32 s29, s25, 0
	s_add_u32 s42, s24, 0xc00000
	s_addc_u32 s43, s25, 0
	s_add_i32 s55, 0, 0x10000
	s_and_b64 s[2:3], s[30:31], exec
	s_cselect_b32 s27, s13, s25
	s_cselect_b32 s44, s12, s24
	s_add_i32 vcc_hi, 0, 0x14000
	v_add_u32_e32 v142, s55, v97
	v_add_u32_e32 v143, vcc_hi, v97
	ds_read_b128 v[0:3], v142
	ds_read_b128 v[4:7], v142 offset:1024
	ds_read_b128 v[8:11], v142 offset:2048
	ds_read_b128 v[12:15], v142 offset:3072
	ds_read_b128 v[16:19], v143
	s_waitcnt lgkmcnt(0)
	ds_read_b128 v[20:23], v143 offset:1024
	ds_read_b128 v[24:27], v143 offset:2048
	ds_read_b128 v[28:31], v143 offset:3072
	v_writelane_b32 v255, s30, 33
	s_and_b64 s[2:3], s[30:31], exec
	s_cselect_b32 s45, s47, s1
	v_writelane_b32 v255, s31, 34
	s_cselect_b32 s49, s46, s0
	s_add_u32 s2, s24, 0x404000
	s_addc_u32 s3, s25, 0
	s_add_i32 s50, s22, 0xc000
	v_lshl_add_u64 v[64:65], s[2:3], 0, v[130:131]
	s_mov_b32 m0, s50
	s_add_i32 s51, s22, 0xe000
	ds_read_b128 v[32:35], v161
	ds_read_b128 v[36:39], v161 offset:1024
	ds_read_b128 v[40:43], v161 offset:2048
	ds_read_b128 v[44:47], v161 offset:3072
	ds_read_b128 v[48:51], v161 offset:4096
	ds_read_b128 v[52:55], v161 offset:5120
	ds_read_b128 v[56:59], v161 offset:6144
	ds_read_b128 v[60:63], v161 offset:7168
	global_load_lds_dwordx4 v[64:65], off
	v_lshl_add_u64 v[64:65], s[2:3], 0, v[134:135]
	s_mov_b32 m0, s51
	s_nop 0
	global_load_lds_dwordx4 v[64:65], off
	s_waitcnt vmcnt(8)
	s_waitcnt lgkmcnt(0)
	s_setprio 1
	s_barrier
	v_mfma_f32_16x16x32_bf16 v[64:67], v[0:3], v[32:35], 0
	v_mfma_f32_16x16x32_bf16 v[68:71], v[8:11], v[32:35], 0
	v_mfma_f32_16x16x32_bf16 v[72:75], v[0:3], v[40:43], 0
	v_mfma_f32_16x16x32_bf16 v[76:79], v[8:11], v[40:43], 0
	v_mfma_f32_16x16x32_bf16 v[80:83], v[0:3], v[48:51], 0
	v_mfma_f32_16x16x32_bf16 v[84:87], v[8:11], v[48:51], 0
	v_mfma_f32_16x16x32_bf16 v[88:91], v[0:3], v[56:59], 0
	v_mfma_f32_16x16x32_bf16 v[92:95], v[8:11], v[56:59], 0
	v_mfma_f32_16x16x32_bf16 v[64:67], v[4:7], v[36:39], v[64:67]
	v_mfma_f32_16x16x32_bf16 v[68:71], v[12:15], v[36:39], v[68:71]
	v_mfma_f32_16x16x32_bf16 v[72:75], v[4:7], v[44:47], v[72:75]
	v_mfma_f32_16x16x32_bf16 v[76:79], v[12:15], v[44:47], v[76:79]
	v_mfma_f32_16x16x32_bf16 v[80:83], v[4:7], v[52:55], v[80:83]
	v_mfma_f32_16x16x32_bf16 v[84:87], v[12:15], v[52:55], v[84:87]
	v_mfma_f32_16x16x32_bf16 v[88:91], v[4:7], v[60:63], v[88:91]
	v_mfma_f32_16x16x32_bf16 v[98:101], v[12:15], v[60:63], v[92:95]
	s_setprio 0
	s_setprio 1
	v_mfma_f32_16x16x32_bf16 v[92:95], v[16:19], v[32:35], 0
	v_mfma_f32_16x16x32_bf16 v[32:35], v[24:27], v[32:35], 0
	v_mfma_f32_16x16x32_bf16 v[106:109], v[20:23], v[36:39], v[92:95]
	v_mfma_f32_16x16x32_bf16 v[32:35], v[28:31], v[36:39], v[32:35]
	v_mfma_f32_16x16x32_bf16 v[36:39], v[16:19], v[40:43], 0
	v_mfma_f32_16x16x32_bf16 v[40:43], v[24:27], v[40:43], 0
	v_mfma_f32_16x16x32_bf16 v[36:39], v[20:23], v[44:47], v[36:39]
	v_mfma_f32_16x16x32_bf16 v[40:43], v[28:31], v[44:47], v[40:43]
	v_mfma_f32_16x16x32_bf16 v[44:47], v[16:19], v[48:51], 0
	v_mfma_f32_16x16x32_bf16 v[48:51], v[24:27], v[48:51], 0
	v_mfma_f32_16x16x32_bf16 v[44:47], v[20:23], v[52:55], v[44:47]
	v_mfma_f32_16x16x32_bf16 v[48:51], v[28:31], v[52:55], v[48:51]
	v_mfma_f32_16x16x32_bf16 v[52:55], v[16:19], v[56:59], 0
	v_mfma_f32_16x16x32_bf16 v[56:59], v[24:27], v[56:59], 0
	v_mfma_f32_16x16x32_bf16 v[52:55], v[20:23], v[60:63], v[52:55]
	v_mfma_f32_16x16x32_bf16 v[56:59], v[28:31], v[60:63], v[56:59]
	s_barrier
	s_setprio 0
	v_lshl_add_u64 v[158:159], s[0:1], 0, v[132:133]
	s_mov_b64 s[2:3], 0x100
	s_add_i32 s55, s55, s10
	v_lshl_add_u64 v[144:145], v[158:159], 0, s[2:3]
	s_mov_b32 m0, s55
	v_lshl_add_u64 v[178:179], s[0:1], 0, v[136:137]
	s_add_i32 vcc_lo, s55, 0x2000
	ds_read_b128 v[60:63], v161 offset:16384
	ds_read_b128 v[92:95], v161 offset:17408
	ds_read_b128 v[102:105], v161 offset:18432
	ds_read_b128 v[110:113], v161 offset:19456
	ds_read_b128 v[114:117], v161 offset:20480
	ds_read_b128 v[118:121], v161 offset:21504
	ds_read_b128 v[122:125], v161 offset:22528
	ds_read_b128 v[126:129], v161 offset:23552
	global_load_lds_dwordx4 v[144:145], off
	v_lshl_add_u64 v[144:145], v[178:179], 0, s[2:3]
	s_add_u32 s2, s0, 0x40100
	s_mov_b32 m0, vcc_lo
	s_addc_u32 s3, s1, 0
	s_add_i32 vcc_hi, vcc_hi, s10
	global_load_lds_dwordx4 v[144:145], off
	v_lshl_add_u64 v[144:145], s[2:3], 0, v[132:133]
	s_mov_b32 m0, vcc_hi
	s_add_i32 s56, vcc_hi, 0x2000
	global_load_lds_dwordx4 v[144:145], off
	v_lshl_add_u64 v[144:145], s[2:3], 0, v[136:137]
	s_mov_b32 m0, s56
	s_nop 0
	global_load_lds_dwordx4 v[144:145], off
	v_lshl_add_u64 v[144:145], s[28:29], 0, v[130:131]
	s_mov_b32 m0, s22
	s_nop 0
	global_load_lds_dwordx4 v[144:145], off
	v_lshl_add_u64 v[144:145], s[28:29], 0, v[134:135]
	s_mov_b32 m0, s23
	s_nop 0
	global_load_lds_dwordx4 v[144:145], off
	s_waitcnt vmcnt(8)
	s_waitcnt lgkmcnt(0)
	s_setprio 1
	s_barrier
	v_mfma_f32_16x16x32_bf16 v[144:147], v[0:3], v[60:63], 0
	v_mfma_f32_16x16x32_bf16 v[154:157], v[0:3], v[102:105], 0
	v_mfma_f32_16x16x32_bf16 v[166:169], v[0:3], v[114:117], 0
	v_mfma_f32_16x16x32_bf16 v[0:3], v[0:3], v[122:125], 0
	v_mfma_f32_16x16x32_bf16 v[146:149], v[4:7], v[92:95], v[144:147]
	v_mfma_f32_16x16x32_bf16 v[154:157], v[4:7], v[110:113], v[154:157]
	v_mfma_f32_16x16x32_bf16 v[166:169], v[4:7], v[118:121], v[166:169]
	v_mfma_f32_16x16x32_bf16 v[0:3], v[4:7], v[126:129], v[0:3]
	v_mfma_f32_16x16x32_bf16 v[4:7], v[8:11], v[122:125], 0
	v_mfma_f32_16x16x32_bf16 v[150:153], v[8:11], v[60:63], 0
	v_mfma_f32_16x16x32_bf16 v[162:165], v[8:11], v[102:105], 0
	v_mfma_f32_16x16x32_bf16 v[170:173], v[8:11], v[114:117], 0
	v_mfma_f32_16x16x32_bf16 v[4:7], v[12:15], v[126:129], v[4:7]
	v_mfma_f32_16x16x32_bf16 v[150:153], v[12:15], v[92:95], v[150:153]
	v_mfma_f32_16x16x32_bf16 v[162:165], v[12:15], v[110:113], v[162:165]
	v_mfma_f32_16x16x32_bf16 v[170:173], v[12:15], v[118:121], v[170:173]
	s_setprio 0
	s_setprio 1
	v_mfma_f32_16x16x32_bf16 v[12:15], v[24:27], v[60:63], 0
	v_mfma_f32_16x16x32_bf16 v[174:177], v[28:31], v[92:95], v[12:15]
	v_mfma_f32_16x16x32_bf16 v[12:15], v[16:19], v[102:105], 0
	v_mfma_f32_16x16x32_bf16 v[180:183], v[20:23], v[110:113], v[12:15]
	v_mfma_f32_16x16x32_bf16 v[12:15], v[24:27], v[102:105], 0
	v_mfma_f32_16x16x32_bf16 v[184:187], v[28:31], v[110:113], v[12:15]
	v_mfma_f32_16x16x32_bf16 v[12:15], v[16:19], v[114:117], 0
	v_mfma_f32_16x16x32_bf16 v[188:191], v[20:23], v[118:121], v[12:15]
	v_mfma_f32_16x16x32_bf16 v[12:15], v[24:27], v[114:117], 0
	v_mfma_f32_16x16x32_bf16 v[8:11], v[16:19], v[60:63], 0
	v_mfma_f32_16x16x32_bf16 v[192:195], v[28:31], v[118:121], v[12:15]
	v_mfma_f32_16x16x32_bf16 v[12:15], v[16:19], v[122:125], 0
	v_mfma_f32_16x16x32_bf16 v[8:11], v[20:23], v[92:95], v[8:11]
	v_mfma_f32_16x16x32_bf16 v[196:199], v[20:23], v[126:129], v[12:15]
	v_mfma_f32_16x16x32_bf16 v[12:15], v[24:27], v[122:125], 0
	v_mfma_f32_16x16x32_bf16 v[200:203], v[28:31], v[126:129], v[12:15]
	s_barrier
	s_setprio 0
	s_add_i32 s30, 0, 0x18000
	s_add_i32 s57, 0, 0x1c000
	v_add_u32_e32 v144, s30, v97
	v_add_u32_e32 v145, s57, v97
	s_nop 0
	ds_read_b128 v[12:15], v144
	ds_read_b128 v[16:19], v144 offset:1024
	ds_read_b128 v[24:27], v144 offset:2048
	ds_read_b128 v[204:207], v144 offset:3072
	ds_read_b128 v[208:211], v145
	ds_read_b128 v[212:215], v145 offset:1024
	ds_read_b128 v[216:219], v145 offset:2048
	ds_read_b128 v[220:223], v145 offset:3072
	s_add_u32 s2, s24, 0x804000
	s_addc_u32 s3, s25, 0
	s_mov_b32 m0, s39
	v_lshl_add_u64 v[92:93], s[2:3], 0, v[130:131]
	ds_read_b128 v[20:23], v161 offset:32768
	ds_read_b128 v[28:31], v161 offset:33792
	ds_read_b128 v[60:63], v161 offset:34816
	ds_read_b128 v[224:227], v161 offset:35840
	ds_read_b128 v[228:231], v161 offset:36864
	ds_read_b128 v[234:237], v161 offset:37888
	ds_read_b128 v[238:241], v161 offset:38912
	ds_read_b128 v[242:245], v161 offset:39936
	global_load_lds_dwordx4 v[92:93], off
	v_lshl_add_u64 v[92:93], s[2:3], 0, v[134:135]
	s_mov_b32 m0, s52
	s_nop 0
	global_load_lds_dwordx4 v[92:93], off
	s_waitcnt vmcnt(8)
	s_waitcnt lgkmcnt(0)
	s_setprio 1
	s_barrier
	v_mfma_f32_16x16x32_bf16 v[64:67], v[12:15], v[20:23], v[64:67]
	v_mfma_f32_16x16x32_bf16 v[126:129], v[16:19], v[28:31], v[64:67]
	v_mfma_f32_16x16x32_bf16 v[64:67], v[24:27], v[20:23], v[68:71]
	v_mfma_f32_16x16x32_bf16 v[118:121], v[204:207], v[28:31], v[64:67]
	v_mfma_f32_16x16x32_bf16 v[64:67], v[12:15], v[60:63], v[72:75]
	v_mfma_f32_16x16x32_bf16 v[110:113], v[16:19], v[224:227], v[64:67]
	v_mfma_f32_16x16x32_bf16 v[64:67], v[24:27], v[60:63], v[76:79]
	v_mfma_f32_16x16x32_bf16 v[102:105], v[204:207], v[224:227], v[64:67]
	v_mfma_f32_16x16x32_bf16 v[64:67], v[12:15], v[228:231], v[80:83]
	v_mfma_f32_16x16x32_bf16 v[92:95], v[16:19], v[234:237], v[64:67]
	v_mfma_f32_16x16x32_bf16 v[64:67], v[24:27], v[228:231], v[84:87]
	v_mfma_f32_16x16x32_bf16 v[84:87], v[204:207], v[234:237], v[64:67]
	v_mfma_f32_16x16x32_bf16 v[64:67], v[12:15], v[238:241], v[88:91]
	v_mfma_f32_16x16x32_bf16 v[76:79], v[16:19], v[242:245], v[64:67]
	v_mfma_f32_16x16x32_bf16 v[64:67], v[24:27], v[238:241], v[98:101]
	v_mfma_f32_16x16x32_bf16 v[68:71], v[204:207], v[242:245], v[64:67]
	s_setprio 0
	s_setprio 1
	v_mfma_f32_16x16x32_bf16 v[64:67], v[208:211], v[20:23], v[106:109]
	v_mfma_f32_16x16x32_bf16 v[20:23], v[216:219], v[20:23], v[32:35]
	v_mfma_f32_16x16x32_bf16 v[114:117], v[220:223], v[28:31], v[20:23]
	v_mfma_f32_16x16x32_bf16 v[20:23], v[208:211], v[60:63], v[36:39]
	v_mfma_f32_16x16x32_bf16 v[106:109], v[212:215], v[224:227], v[20:23]
	v_mfma_f32_16x16x32_bf16 v[20:23], v[216:219], v[60:63], v[40:43]
	v_mfma_f32_16x16x32_bf16 v[98:101], v[220:223], v[224:227], v[20:23]
	v_mfma_f32_16x16x32_bf16 v[20:23], v[208:211], v[228:231], v[44:47]
	v_mfma_f32_16x16x32_bf16 v[88:91], v[212:215], v[234:237], v[20:23]
	v_mfma_f32_16x16x32_bf16 v[20:23], v[216:219], v[228:231], v[48:51]
	v_mfma_f32_16x16x32_bf16 v[80:83], v[220:223], v[234:237], v[20:23]
	v_mfma_f32_16x16x32_bf16 v[20:23], v[208:211], v[238:241], v[52:55]
	v_mfma_f32_16x16x32_bf16 v[72:75], v[212:215], v[242:245], v[20:23]
	v_mfma_f32_16x16x32_bf16 v[20:23], v[216:219], v[238:241], v[56:59]
	v_mfma_f32_16x16x32_bf16 v[122:125], v[212:215], v[28:31], v[64:67]
	v_mfma_f32_16x16x32_bf16 v[64:67], v[220:223], v[242:245], v[20:23]
	s_barrier
; template <class Epi, class Sched, bool ALIGN_EPI = false, bool SP2 = false>
; __device__ __forceinline__ void gemm_phase(PG8_LAS unsigned char* lds, const Gemm g, const Sched& S, const Epi& E) {
;     ...
;         if constexpr (Epi::PEEL) {
;             const char* a1 = cA + kstepA; const char* a2 = cA + 2 * kstepA; const char* b2 = cB + 2 * kstepB; const char* a3 = a2 + kstepA; const char* b3 = b2 + kstepB;
;             PG8_ITER(8);
;         }
;         for (int t = (Epi::PEEL ? 2 : 0); t < nt; t += 2) {
;             const bool last = (t == nt - 2);
;             const char* a1 = cA + (size_t)(t + 1) * kstepA;
;             const char* a2 = last ? nA : cA + (size_t)(t + 2) * kstepA; const char* b2 = last ? nB : cB + (size_t)(t + 2) * kstepB;
;             const char* a3 = a2 + kstepA; const char* b3 = b2 + kstepB;
;             PG8_ITER(8);
	s_setprio 0
	s_mov_b64 s[2:3], 0x180
	s_add_i32 s30, s30, s10
	s_nop 1
	v_lshl_add_u64 v[20:21], v[158:159], 0, s[2:3]
	s_mov_b32 m0, s30
	s_add_i32 s31, s30, 0x2000
	ds_read_b128 v[32:35], v161 offset:49152
	ds_read_b128 v[40:43], v161 offset:50176
	ds_read_b128 v[224:227], v161 offset:51200
	ds_read_b128 v[228:231], v161 offset:52224
	ds_read_b128 v[234:237], v161 offset:53248
	ds_read_b128 v[238:241], v161 offset:54272
	ds_read_b128 v[242:245], v161 offset:55296
	ds_read_b128 v[246:249], v161 offset:56320
	global_load_lds_dwordx4 v[20:21], off
	v_lshl_add_u64 v[20:21], v[178:179], 0, s[2:3]
	s_add_u32 s2, s0, 0x40180
	s_mov_b32 m0, s31
	s_addc_u32 s3, s1, 0
	s_add_i32 s57, s57, s10
	global_load_lds_dwordx4 v[20:21], off
	v_lshl_add_u64 v[20:21], s[2:3], 0, v[132:133]
	s_mov_b32 m0, s57
	s_add_i32 s96, s57, 0x2000
	global_load_lds_dwordx4 v[20:21], off
	v_lshl_add_u64 v[20:21], s[2:3], 0, v[136:137]
	s_mov_b32 m0, s96
	s_nop 0
	global_load_lds_dwordx4 v[20:21], off
	v_lshl_add_u64 v[20:21], s[42:43], 0, v[130:131]
	s_mov_b32 m0, s11
	s_nop 0
	global_load_lds_dwordx4 v[20:21], off
	v_lshl_add_u64 v[20:21], s[42:43], 0, v[134:135]
	s_mov_b32 m0, s19
	s_nop 0
	global_load_lds_dwordx4 v[20:21], off
	s_waitcnt vmcnt(8)
	s_waitcnt lgkmcnt(0)
	s_setprio 1
	s_barrier
	v_mfma_f32_16x16x32_bf16 v[20:23], v[12:15], v[32:35], v[146:149]
	v_mfma_f32_16x16x32_bf16 v[60:63], v[16:19], v[40:43], v[20:23]
	v_mfma_f32_16x16x32_bf16 v[20:23], v[24:27], v[32:35], v[150:153]
	v_mfma_f32_16x16x32_bf16 v[52:55], v[204:207], v[40:43], v[20:23]
	v_mfma_f32_16x16x32_bf16 v[20:23], v[12:15], v[224:227], v[154:157]
	v_mfma_f32_16x16x32_bf16 v[44:47], v[16:19], v[228:231], v[20:23]
	v_mfma_f32_16x16x32_bf16 v[20:23], v[24:27], v[224:227], v[162:165]
	v_mfma_f32_16x16x32_bf16 v[36:39], v[204:207], v[228:231], v[20:23]
	v_mfma_f32_16x16x32_bf16 v[20:23], v[12:15], v[234:237], v[166:169]
	v_mfma_f32_16x16x32_bf16 v[0:3], v[12:15], v[242:245], v[0:3]
	v_mfma_f32_16x16x32_bf16 v[28:31], v[16:19], v[238:241], v[20:23]
	v_mfma_f32_16x16x32_bf16 v[20:23], v[24:27], v[234:237], v[170:173]
	v_mfma_f32_16x16x32_bf16 v[12:15], v[16:19], v[246:249], v[0:3]
	v_mfma_f32_16x16x32_bf16 v[0:3], v[24:27], v[242:245], v[4:7]
	v_mfma_f32_16x16x32_bf16 v[20:23], v[204:207], v[238:241], v[20:23]
	v_mfma_f32_16x16x32_bf16 v[4:7], v[204:207], v[246:249], v[0:3]
	s_setprio 0
	s_setprio 1
	v_mfma_f32_16x16x32_bf16 v[0:3], v[208:211], v[32:35], v[8:11]
	v_mfma_f32_16x16x32_bf16 v[56:59], v[212:215], v[40:43], v[0:3]
	v_mfma_f32_16x16x32_bf16 v[0:3], v[216:219], v[32:35], v[174:177]
	v_mfma_f32_16x16x32_bf16 v[48:51], v[220:223], v[40:43], v[0:3]
	v_mfma_f32_16x16x32_bf16 v[0:3], v[208:211], v[224:227], v[180:183]
	v_mfma_f32_16x16x32_bf16 v[40:43], v[212:215], v[228:231], v[0:3]
	v_mfma_f32_16x16x32_bf16 v[0:3], v[216:219], v[224:227], v[184:187]
	v_mfma_f32_16x16x32_bf16 v[32:35], v[220:223], v[228:231], v[0:3]
	v_mfma_f32_16x16x32_bf16 v[0:3], v[208:211], v[234:237], v[188:191]
	v_mfma_f32_16x16x32_bf16 v[24:27], v[212:215], v[238:241], v[0:3]
	v_mfma_f32_16x16x32_bf16 v[0:3], v[216:219], v[234:237], v[192:195]
	v_mfma_f32_16x16x32_bf16 v[16:19], v[220:223], v[238:241], v[0:3]
	v_mfma_f32_16x16x32_bf16 v[0:3], v[208:211], v[242:245], v[196:199]
	v_mfma_f32_16x16x32_bf16 v[8:11], v[212:215], v[246:249], v[0:3]
	v_mfma_f32_16x16x32_bf16 v[0:3], v[216:219], v[242:245], v[200:203]
	v_mfma_f32_16x16x32_bf16 v[0:3], v[220:223], v[246:249], v[0:3]
	s_barrier
	s_setprio 0
	s_add_u32 s3, s0, 0x200
	s_addc_u32 s2, s1, 0
	s_add_u32 s0, s24, 0xc04000
	s_addc_u32 s1, s25, 0
	s_mov_b32 s18, 0
.LBB0_161:
	ds_read_b128 v[146:149], v142
	ds_read_b128 v[150:153], v142 offset:1024
	ds_read_b128 v[154:157], v142 offset:2048
	ds_read_b128 v[162:165], v142 offset:3072
	ds_read_b128 v[166:169], v143
	ds_read_b128 v[170:173], v143 offset:1024
	ds_read_b128 v[174:177], v143 offset:2048
	ds_read_b128 v[180:183], v143 offset:3072
	s_add_u32 s8, s0, 0x3fc000
	s_addc_u32 s9, s1, 0
	s_cmp_eq_u32 s18, 12
	s_cselect_b32 s28, s44, s8
	s_cselect_b32 s29, s27, s9
	s_cselect_b32 s42, s49, s3
	s_cselect_b32 s43, s45, s2
	s_add_u32 s24, s28, 0x400000
	s_addc_u32 s25, s29, 0
	s_mov_b32 m0, s50
	v_lshl_add_u64 v[158:159], s[0:1], 0, v[140:141]
	ds_read_b128 v[184:187], v161
	ds_read_b128 v[188:191], v161 offset:1024
	ds_read_b128 v[192:195], v161 offset:2048
	ds_read_b128 v[196:199], v161 offset:3072
	ds_read_b128 v[200:203], v161 offset:4096
	ds_read_b128 v[204:207], v161 offset:5120
	ds_read_b128 v[208:211], v161 offset:6144
	ds_read_b128 v[212:215], v161 offset:7168
	global_load_lds_dwordx4 v[158:159], off
	v_lshl_add_u64 v[158:159], s[0:1], 0, v[138:139]
	s_mov_b32 m0, s51
	s_nop 0
	global_load_lds_dwordx4 v[158:159], off
	s_waitcnt vmcnt(8)
	s_waitcnt lgkmcnt(0)
	s_setprio 1
	s_barrier
	v_mfma_f32_16x16x32_bf16 v[126:129], v[146:149], v[184:187], v[126:129]
	v_mfma_f32_16x16x32_bf16 v[118:121], v[154:157], v[184:187], v[118:121]
	v_mfma_f32_16x16x32_bf16 v[110:113], v[146:149], v[192:195], v[110:113]
	v_mfma_f32_16x16x32_bf16 v[102:105], v[154:157], v[192:195], v[102:105]
	v_mfma_f32_16x16x32_bf16 v[92:95], v[146:149], v[200:203], v[92:95]
	v_mfma_f32_16x16x32_bf16 v[84:87], v[154:157], v[200:203], v[84:87]
	v_mfma_f32_16x16x32_bf16 v[76:79], v[146:149], v[208:211], v[76:79]
	v_mfma_f32_16x16x32_bf16 v[68:71], v[154:157], v[208:211], v[68:71]
	v_mfma_f32_16x16x32_bf16 v[126:129], v[150:153], v[188:191], v[126:129]
	v_mfma_f32_16x16x32_bf16 v[118:121], v[162:165], v[188:191], v[118:121]
	v_mfma_f32_16x16x32_bf16 v[110:113], v[150:153], v[196:199], v[110:113]
	v_mfma_f32_16x16x32_bf16 v[102:105], v[162:165], v[196:199], v[102:105]
	v_mfma_f32_16x16x32_bf16 v[92:95], v[150:153], v[204:207], v[92:95]
	v_mfma_f32_16x16x32_bf16 v[84:87], v[162:165], v[204:207], v[84:87]
	v_mfma_f32_16x16x32_bf16 v[76:79], v[150:153], v[212:215], v[76:79]
	v_mfma_f32_16x16x32_bf16 v[68:71], v[162:165], v[212:215], v[68:71]
	s_setprio 0
	s_setprio 1
	v_mfma_f32_16x16x32_bf16 v[122:125], v[166:169], v[184:187], v[122:125]
	v_mfma_f32_16x16x32_bf16 v[114:117], v[174:177], v[184:187], v[114:117]
	v_mfma_f32_16x16x32_bf16 v[106:109], v[166:169], v[192:195], v[106:109]
	v_mfma_f32_16x16x32_bf16 v[98:101], v[174:177], v[192:195], v[98:101]
	v_mfma_f32_16x16x32_bf16 v[88:91], v[166:169], v[200:203], v[88:91]
	v_mfma_f32_16x16x32_bf16 v[80:83], v[174:177], v[200:203], v[80:83]
	v_mfma_f32_16x16x32_bf16 v[72:75], v[166:169], v[208:211], v[72:75]
	v_mfma_f32_16x16x32_bf16 v[64:67], v[174:177], v[208:211], v[64:67]
	v_mfma_f32_16x16x32_bf16 v[122:125], v[170:173], v[188:191], v[122:125]
	v_mfma_f32_16x16x32_bf16 v[114:117], v[180:183], v[188:191], v[114:117]
	v_mfma_f32_16x16x32_bf16 v[106:109], v[170:173], v[196:199], v[106:109]
	v_mfma_f32_16x16x32_bf16 v[98:101], v[180:183], v[196:199], v[98:101]
	v_mfma_f32_16x16x32_bf16 v[88:91], v[170:173], v[204:207], v[88:91]
	v_mfma_f32_16x16x32_bf16 v[80:83], v[180:183], v[204:207], v[80:83]
	v_mfma_f32_16x16x32_bf16 v[72:75], v[170:173], v[212:215], v[72:75]
	v_mfma_f32_16x16x32_bf16 v[64:67], v[180:183], v[212:215], v[64:67]
	s_barrier
	s_setprio 0
	s_mov_b32 m0, s55
	v_lshl_add_u64 v[158:159], s[42:43], 0, v[132:133]
	s_add_u32 s8, s42, 0x40000
	ds_read_b128 v[184:187], v161 offset:16384
	ds_read_b128 v[188:191], v161 offset:17408
	ds_read_b128 v[192:195], v161 offset:18432
	ds_read_b128 v[196:199], v161 offset:19456
	ds_read_b128 v[200:203], v161 offset:20480
	ds_read_b128 v[204:207], v161 offset:21504
	ds_read_b128 v[208:211], v161 offset:22528
	ds_read_b128 v[212:215], v161 offset:23552
	global_load_lds_dwordx4 v[158:159], off
	v_lshl_add_u64 v[178:179], s[42:43], 0, v[136:137]
	s_mov_b32 m0, vcc_lo
	s_addc_u32 s9, s43, 0
	global_load_lds_dwordx4 v[178:179], off
	v_lshl_add_u64 v[216:217], s[8:9], 0, v[132:133]
	s_mov_b32 m0, vcc_hi
	s_nop 0
	global_load_lds_dwordx4 v[216:217], off
	v_lshl_add_u64 v[216:217], s[8:9], 0, v[136:137]
	s_mov_b32 m0, s56
	s_nop 0
	global_load_lds_dwordx4 v[216:217], off
	v_lshl_add_u64 v[216:217], s[28:29], 0, v[130:131]
	s_mov_b32 m0, s22
	s_nop 0
	global_load_lds_dwordx4 v[216:217], off
	v_lshl_add_u64 v[216:217], s[28:29], 0, v[134:135]
	s_mov_b32 m0, s23
	s_nop 0
	global_load_lds_dwordx4 v[216:217], off
	s_waitcnt vmcnt(8)
	s_waitcnt lgkmcnt(0)
	s_setprio 1
	s_barrier
	v_mfma_f32_16x16x32_bf16 v[60:63], v[146:149], v[184:187], v[60:63]
	v_mfma_f32_16x16x32_bf16 v[52:55], v[154:157], v[184:187], v[52:55]
	v_mfma_f32_16x16x32_bf16 v[44:47], v[146:149], v[192:195], v[44:47]
	v_mfma_f32_16x16x32_bf16 v[36:39], v[154:157], v[192:195], v[36:39]
	v_mfma_f32_16x16x32_bf16 v[28:31], v[146:149], v[200:203], v[28:31]
	v_mfma_f32_16x16x32_bf16 v[20:23], v[154:157], v[200:203], v[20:23]
	v_mfma_f32_16x16x32_bf16 v[12:15], v[146:149], v[208:211], v[12:15]
	v_mfma_f32_16x16x32_bf16 v[4:7], v[154:157], v[208:211], v[4:7]
	v_mfma_f32_16x16x32_bf16 v[60:63], v[150:153], v[188:191], v[60:63]
	v_mfma_f32_16x16x32_bf16 v[52:55], v[162:165], v[188:191], v[52:55]
	v_mfma_f32_16x16x32_bf16 v[44:47], v[150:153], v[196:199], v[44:47]
	v_mfma_f32_16x16x32_bf16 v[36:39], v[162:165], v[196:199], v[36:39]
	v_mfma_f32_16x16x32_bf16 v[28:31], v[150:153], v[204:207], v[28:31]
	v_mfma_f32_16x16x32_bf16 v[20:23], v[162:165], v[204:207], v[20:23]
	v_mfma_f32_16x16x32_bf16 v[12:15], v[150:153], v[212:215], v[12:15]
	v_mfma_f32_16x16x32_bf16 v[4:7], v[162:165], v[212:215], v[4:7]
	s_setprio 0
	s_setprio 1
	v_mfma_f32_16x16x32_bf16 v[56:59], v[166:169], v[184:187], v[56:59]
	v_mfma_f32_16x16x32_bf16 v[48:51], v[174:177], v[184:187], v[48:51]
	v_mfma_f32_16x16x32_bf16 v[40:43], v[166:169], v[192:195], v[40:43]
	v_mfma_f32_16x16x32_bf16 v[32:35], v[174:177], v[192:195], v[32:35]
	v_mfma_f32_16x16x32_bf16 v[24:27], v[166:169], v[200:203], v[24:27]
	v_mfma_f32_16x16x32_bf16 v[16:19], v[174:177], v[200:203], v[16:19]
	v_mfma_f32_16x16x32_bf16 v[8:11], v[166:169], v[208:211], v[8:11]
	v_mfma_f32_16x16x32_bf16 v[0:3], v[174:177], v[208:211], v[0:3]
	v_mfma_f32_16x16x32_bf16 v[56:59], v[170:173], v[188:191], v[56:59]
	v_mfma_f32_16x16x32_bf16 v[48:51], v[180:183], v[188:191], v[48:51]
	v_mfma_f32_16x16x32_bf16 v[40:43], v[170:173], v[196:199], v[40:43]
	v_mfma_f32_16x16x32_bf16 v[32:35], v[180:183], v[196:199], v[32:35]
	v_mfma_f32_16x16x32_bf16 v[24:27], v[170:173], v[204:207], v[24:27]
	v_mfma_f32_16x16x32_bf16 v[16:19], v[180:183], v[204:207], v[16:19]
	v_mfma_f32_16x16x32_bf16 v[8:11], v[170:173], v[212:215], v[8:11]
	v_mfma_f32_16x16x32_bf16 v[0:3], v[180:183], v[212:215], v[0:3]
	s_barrier
	s_setprio 0
	ds_read_b128 v[146:149], v144
	ds_read_b128 v[150:153], v144 offset:1024
	ds_read_b128 v[154:157], v144 offset:2048
	ds_read_b128 v[162:165], v144 offset:3072
	ds_read_b128 v[166:169], v145
	ds_read_b128 v[170:173], v145 offset:1024
	ds_read_b128 v[174:177], v145 offset:2048
	ds_read_b128 v[180:183], v145 offset:3072
	s_add_u32 s8, s28, 0x4000
	s_addc_u32 s9, s29, 0
	s_mov_b32 m0, s39
	v_lshl_add_u64 v[216:217], s[8:9], 0, v[130:131]
	ds_read_b128 v[184:187], v161 offset:32768
	ds_read_b128 v[188:191], v161 offset:33792
	ds_read_b128 v[192:195], v161 offset:34816
	ds_read_b128 v[196:199], v161 offset:35840
	ds_read_b128 v[200:203], v161 offset:36864
	ds_read_b128 v[204:207], v161 offset:37888
	ds_read_b128 v[208:211], v161 offset:38912
	ds_read_b128 v[212:215], v161 offset:39936
	global_load_lds_dwordx4 v[216:217], off
	v_lshl_add_u64 v[216:217], s[8:9], 0, v[134:135]
	s_mov_b32 m0, s52
	s_nop 0
	global_load_lds_dwordx4 v[216:217], off
	s_waitcnt vmcnt(8)
	s_waitcnt lgkmcnt(0)
	s_setprio 1
	s_barrier
	v_mfma_f32_16x16x32_bf16 v[126:129], v[146:149], v[184:187], v[126:129]
	v_mfma_f32_16x16x32_bf16 v[118:121], v[154:157], v[184:187], v[118:121]
	v_mfma_f32_16x16x32_bf16 v[110:113], v[146:149], v[192:195], v[110:113]
	v_mfma_f32_16x16x32_bf16 v[102:105], v[154:157], v[192:195], v[102:105]
	v_mfma_f32_16x16x32_bf16 v[92:95], v[146:149], v[200:203], v[92:95]
	v_mfma_f32_16x16x32_bf16 v[84:87], v[154:157], v[200:203], v[84:87]
	v_mfma_f32_16x16x32_bf16 v[76:79], v[146:149], v[208:211], v[76:79]
	v_mfma_f32_16x16x32_bf16 v[68:71], v[154:157], v[208:211], v[68:71]
	v_mfma_f32_16x16x32_bf16 v[126:129], v[150:153], v[188:191], v[126:129]
	v_mfma_f32_16x16x32_bf16 v[118:121], v[162:165], v[188:191], v[118:121]
	v_mfma_f32_16x16x32_bf16 v[110:113], v[150:153], v[196:199], v[110:113]
	v_mfma_f32_16x16x32_bf16 v[102:105], v[162:165], v[196:199], v[102:105]
	v_mfma_f32_16x16x32_bf16 v[92:95], v[150:153], v[204:207], v[92:95]
	v_mfma_f32_16x16x32_bf16 v[84:87], v[162:165], v[204:207], v[84:87]
	v_mfma_f32_16x16x32_bf16 v[76:79], v[150:153], v[212:215], v[76:79]
	v_mfma_f32_16x16x32_bf16 v[68:71], v[162:165], v[212:215], v[68:71]
	s_setprio 0
	s_setprio 1
	v_mfma_f32_16x16x32_bf16 v[122:125], v[166:169], v[184:187], v[122:125]
	v_mfma_f32_16x16x32_bf16 v[114:117], v[174:177], v[184:187], v[114:117]
	v_mfma_f32_16x16x32_bf16 v[106:109], v[166:169], v[192:195], v[106:109]
	v_mfma_f32_16x16x32_bf16 v[98:101], v[174:177], v[192:195], v[98:101]
	v_mfma_f32_16x16x32_bf16 v[88:91], v[166:169], v[200:203], v[88:91]
	v_mfma_f32_16x16x32_bf16 v[80:83], v[174:177], v[200:203], v[80:83]
	v_mfma_f32_16x16x32_bf16 v[72:75], v[166:169], v[208:211], v[72:75]
	v_mfma_f32_16x16x32_bf16 v[64:67], v[174:177], v[208:211], v[64:67]
	v_mfma_f32_16x16x32_bf16 v[122:125], v[170:173], v[188:191], v[122:125]
	v_mfma_f32_16x16x32_bf16 v[114:117], v[180:183], v[188:191], v[114:117]
	v_mfma_f32_16x16x32_bf16 v[106:109], v[170:173], v[196:199], v[106:109]
	v_mfma_f32_16x16x32_bf16 v[98:101], v[180:183], v[196:199], v[98:101]
	v_mfma_f32_16x16x32_bf16 v[88:91], v[170:173], v[204:207], v[88:91]
	v_mfma_f32_16x16x32_bf16 v[80:83], v[180:183], v[204:207], v[80:83]
	v_mfma_f32_16x16x32_bf16 v[72:75], v[170:173], v[212:215], v[72:75]
	v_mfma_f32_16x16x32_bf16 v[64:67], v[180:183], v[212:215], v[64:67]
	s_barrier
; template <class Epi, class Sched, bool ALIGN_EPI = false, bool SP2 = false>
; __device__ __forceinline__ void gemm_phase(PG8_LAS unsigned char* lds, const Gemm g, const Sched& S, const Epi& E) {
;     ...
;         if constexpr (Epi::PEEL) {
;             const char* a1 = cA + kstepA; const char* a2 = cA + 2 * kstepA; const char* b2 = cB + 2 * kstepB; const char* a3 = a2 + kstepA; const char* b3 = b2 + kstepB;
;             PG8_ITER(8);
;         }
;         for (int t = (Epi::PEEL ? 2 : 0); t < nt; t += 2) {
;             const bool last = (t == nt - 2);
;             const char* a1 = cA + (size_t)(t + 1) * kstepA;
;             const char* a2 = last ? nA : cA + (size_t)(t + 2) * kstepA; const char* b2 = last ? nB : cB + (size_t)(t + 2) * kstepB;
;             const char* a3 = a2 + kstepA; const char* b3 = b2 + kstepB;
;             PG8_ITER(8);
;         }
	s_setprio 0
	s_mov_b32 m0, s30
	v_lshl_add_u64 v[158:159], v[158:159], 0, s[36:37]
	s_add_u32 s8, s42, 0x40080
	ds_read_b128 v[184:187], v161 offset:49152
	ds_read_b128 v[188:191], v161 offset:50176
	ds_read_b128 v[192:195], v161 offset:51200
	ds_read_b128 v[196:199], v161 offset:52224
	ds_read_b128 v[200:203], v161 offset:53248
	ds_read_b128 v[204:207], v161 offset:54272
	ds_read_b128 v[208:211], v161 offset:55296
	ds_read_b128 v[212:215], v161 offset:56320
	global_load_lds_dwordx4 v[158:159], off
	v_lshl_add_u64 v[158:159], v[178:179], 0, s[36:37]
	s_mov_b32 m0, s31
	s_addc_u32 s9, s43, 0
	global_load_lds_dwordx4 v[158:159], off
	v_lshl_add_u64 v[158:159], s[8:9], 0, v[132:133]
	s_mov_b32 m0, s57
	s_nop 0
	global_load_lds_dwordx4 v[158:159], off
	v_lshl_add_u64 v[158:159], s[8:9], 0, v[136:137]
	s_mov_b32 m0, s96
	s_nop 0
	global_load_lds_dwordx4 v[158:159], off
	v_lshl_add_u64 v[158:159], s[24:25], 0, v[130:131]
	s_mov_b32 m0, s11
	s_nop 0
	global_load_lds_dwordx4 v[158:159], off
	v_lshl_add_u64 v[158:159], s[24:25], 0, v[134:135]
	s_mov_b32 m0, s19
	s_nop 0
	global_load_lds_dwordx4 v[158:159], off
	s_waitcnt vmcnt(8)
	s_waitcnt lgkmcnt(0)
	s_setprio 1
	s_barrier
	v_mfma_f32_16x16x32_bf16 v[60:63], v[146:149], v[184:187], v[60:63]
	v_mfma_f32_16x16x32_bf16 v[52:55], v[154:157], v[184:187], v[52:55]
	v_mfma_f32_16x16x32_bf16 v[44:47], v[146:149], v[192:195], v[44:47]
	v_mfma_f32_16x16x32_bf16 v[36:39], v[154:157], v[192:195], v[36:39]
	v_mfma_f32_16x16x32_bf16 v[28:31], v[146:149], v[200:203], v[28:31]
	v_mfma_f32_16x16x32_bf16 v[20:23], v[154:157], v[200:203], v[20:23]
	v_mfma_f32_16x16x32_bf16 v[12:15], v[146:149], v[208:211], v[12:15]
	v_mfma_f32_16x16x32_bf16 v[4:7], v[154:157], v[208:211], v[4:7]
	v_mfma_f32_16x16x32_bf16 v[60:63], v[150:153], v[188:191], v[60:63]
	v_mfma_f32_16x16x32_bf16 v[52:55], v[162:165], v[188:191], v[52:55]
	v_mfma_f32_16x16x32_bf16 v[44:47], v[150:153], v[196:199], v[44:47]
	v_mfma_f32_16x16x32_bf16 v[36:39], v[162:165], v[196:199], v[36:39]
	v_mfma_f32_16x16x32_bf16 v[28:31], v[150:153], v[204:207], v[28:31]
	v_mfma_f32_16x16x32_bf16 v[20:23], v[162:165], v[204:207], v[20:23]
	v_mfma_f32_16x16x32_bf16 v[12:15], v[150:153], v[212:215], v[12:15]
	v_mfma_f32_16x16x32_bf16 v[4:7], v[162:165], v[212:215], v[4:7]
	s_setprio 0
	s_setprio 1
	v_mfma_f32_16x16x32_bf16 v[56:59], v[166:169], v[184:187], v[56:59]
	v_mfma_f32_16x16x32_bf16 v[48:51], v[174:177], v[184:187], v[48:51]
	v_mfma_f32_16x16x32_bf16 v[40:43], v[166:169], v[192:195], v[40:43]
	v_mfma_f32_16x16x32_bf16 v[32:35], v[174:177], v[192:195], v[32:35]
	v_mfma_f32_16x16x32_bf16 v[24:27], v[166:169], v[200:203], v[24:27]
	v_mfma_f32_16x16x32_bf16 v[16:19], v[174:177], v[200:203], v[16:19]
	v_mfma_f32_16x16x32_bf16 v[8:11], v[166:169], v[208:211], v[8:11]
	v_mfma_f32_16x16x32_bf16 v[0:3], v[174:177], v[208:211], v[0:3]
	v_mfma_f32_16x16x32_bf16 v[56:59], v[170:173], v[188:191], v[56:59]
	v_mfma_f32_16x16x32_bf16 v[48:51], v[180:183], v[188:191], v[48:51]
	v_mfma_f32_16x16x32_bf16 v[40:43], v[170:173], v[196:199], v[40:43]
	v_mfma_f32_16x16x32_bf16 v[32:35], v[180:183], v[196:199], v[32:35]
	v_mfma_f32_16x16x32_bf16 v[24:27], v[170:173], v[204:207], v[24:27]
	v_mfma_f32_16x16x32_bf16 v[16:19], v[180:183], v[204:207], v[16:19]
	v_mfma_f32_16x16x32_bf16 v[8:11], v[170:173], v[212:215], v[8:11]
	v_mfma_f32_16x16x32_bf16 v[0:3], v[180:183], v[212:215], v[0:3]
	s_barrier
	s_setprio 0
	s_add_i32 s18, s18, 2
	s_add_u32 s3, s3, 0x100
	s_addc_u32 s2, s2, 0
	s_add_u32 s0, s0, 0x800000
	s_addc_u32 s1, s1, 0
	s_cmp_gt_u32 s18, 13
	s_cbranch_scc0 .LBB0_161
	v_readlane_b32 s0, v255, 45
	v_readlane_b32 s1, v255, 46
	s_and_b64 vcc, exec, s[0:1]
	s_cbranch_vccz .LBB0_164
	s_barrier

; template <class Epi, class Sched, bool ALIGN_EPI = false, bool SP2 = false>
; __device__ __forceinline__ void gemm_phase(PG8_LAS unsigned char* lds, const Gemm g, const Sched& S, const Epi& E) {
;     ...
;         const bool has_next = S.next(ui + 1, nxt);
;         const char* nA = has_next ? (const char*)g.A + (size_t)nxt.pm * tstepA : cA; const char* nB = has_next ? (const char*)g.Bt + (size_t)nxt.pn * tstepB : cB;
.LBB0_249:
	s_ashr_i32 s49, s48, 31
	s_lshl_b64 s[2:3], s[48:49], 15
	v_readlane_b32 s11, v255, 15
	s_add_u32 s50, s11, s2
	v_readlane_b32 s2, v255, 16
	s_addc_u32 s51, s2, s3
	s_ashr_i32 s47, s46, 31
	s_lshl_b64 s[2:3], s[46:47], 19
	s_add_u32 s52, s38, s2
	s_addc_u32 s53, s19, s3
	s_add_u32 s28, s42, 0x800000
	s_addc_u32 s29, s43, 0
	s_add_u32 s44, s42, 0xc00000
	s_addc_u32 s45, s43, 0
	s_add_i32 s99, 0, 0x10000
	s_and_b64 s[2:3], s[40:41], exec
	s_cselect_b32 s27, s51, s43
	s_cselect_b32 s47, s50, s42
	s_add_i32 vcc_hi, 0, 0x14000
	v_add_u32_e32 v130, s99, v97
	v_add_u32_e32 v131, vcc_hi, v97
	ds_read_b128 v[0:3], v130
	ds_read_b128 v[4:7], v130 offset:1024
	ds_read_b128 v[8:11], v130 offset:2048
	ds_read_b128 v[12:15], v130 offset:3072
	ds_read_b128 v[16:19], v131
	s_waitcnt lgkmcnt(0)
	ds_read_b128 v[20:23], v131 offset:1024
	ds_read_b128 v[24:27], v131 offset:2048
	ds_read_b128 v[28:31], v131 offset:3072
	s_and_b64 s[2:3], s[40:41], exec
	s_cselect_b32 s49, s53, s25
	s_cselect_b32 s54, s52, s24
	s_add_u32 s2, s42, 0x404000
	s_addc_u32 s3, s43, 0
	s_add_i32 s55, s22, 0xc000
	v_lshl_add_u64 v[64:65], s[2:3], 0, v[134:135]
	s_mov_b32 m0, s55
	s_add_i32 s98, s22, 0xe000
	ds_read_b128 v[32:35], v151
	ds_read_b128 v[36:39], v151 offset:1024
	ds_read_b128 v[40:43], v151 offset:2048
	ds_read_b128 v[44:47], v151 offset:3072
	ds_read_b128 v[48:51], v151 offset:4096
	ds_read_b128 v[52:55], v151 offset:5120
	ds_read_b128 v[56:59], v151 offset:6144
	ds_read_b128 v[60:63], v151 offset:7168
	global_load_lds_dwordx4 v[64:65], off
	v_lshl_add_u64 v[64:65], s[2:3], 0, v[138:139]
	s_mov_b32 m0, s98
	s_nop 0
	global_load_lds_dwordx4 v[64:65], off
	s_waitcnt vmcnt(8)
	s_waitcnt lgkmcnt(0)
	s_setprio 1
	s_barrier
	v_mfma_f32_16x16x32_bf16 v[84:87], v[8:11], v[48:51], 0
	v_mfma_f32_16x16x32_bf16 v[88:91], v[12:15], v[52:55], v[84:87]
	v_mfma_f32_16x16x32_bf16 v[84:87], v[0:3], v[56:59], 0
	v_mfma_f32_16x16x32_bf16 v[64:67], v[0:3], v[32:35], 0
	v_mfma_f32_16x16x32_bf16 v[68:71], v[8:11], v[32:35], 0
	v_mfma_f32_16x16x32_bf16 v[72:75], v[0:3], v[40:43], 0
	v_mfma_f32_16x16x32_bf16 v[76:79], v[8:11], v[40:43], 0
	v_mfma_f32_16x16x32_bf16 v[80:83], v[0:3], v[48:51], 0
	v_mfma_f32_16x16x32_bf16 v[92:95], v[4:7], v[60:63], v[84:87]
	v_mfma_f32_16x16x32_bf16 v[84:87], v[8:11], v[56:59], 0
	v_mfma_f32_16x16x32_bf16 v[64:67], v[4:7], v[36:39], v[64:67]
	v_mfma_f32_16x16x32_bf16 v[68:71], v[12:15], v[36:39], v[68:71]
	v_mfma_f32_16x16x32_bf16 v[72:75], v[4:7], v[44:47], v[72:75]
	v_mfma_f32_16x16x32_bf16 v[76:79], v[12:15], v[44:47], v[76:79]
	v_mfma_f32_16x16x32_bf16 v[80:83], v[4:7], v[52:55], v[80:83]
	v_mfma_f32_16x16x32_bf16 v[106:109], v[12:15], v[60:63], v[84:87]
	s_setprio 0
	s_setprio 1
	v_mfma_f32_16x16x32_bf16 v[84:87], v[16:19], v[32:35], 0
	v_mfma_f32_16x16x32_bf16 v[32:35], v[24:27], v[32:35], 0
	v_mfma_f32_16x16x32_bf16 v[110:113], v[20:23], v[36:39], v[84:87]
	v_mfma_f32_16x16x32_bf16 v[32:35], v[28:31], v[36:39], v[32:35]
	v_mfma_f32_16x16x32_bf16 v[36:39], v[16:19], v[40:43], 0
	v_mfma_f32_16x16x32_bf16 v[40:43], v[24:27], v[40:43], 0
	v_mfma_f32_16x16x32_bf16 v[36:39], v[20:23], v[44:47], v[36:39]
	v_mfma_f32_16x16x32_bf16 v[40:43], v[28:31], v[44:47], v[40:43]
	v_mfma_f32_16x16x32_bf16 v[44:47], v[16:19], v[48:51], 0
	v_mfma_f32_16x16x32_bf16 v[48:51], v[24:27], v[48:51], 0
	v_mfma_f32_16x16x32_bf16 v[44:47], v[20:23], v[52:55], v[44:47]
	v_mfma_f32_16x16x32_bf16 v[48:51], v[28:31], v[52:55], v[48:51]
	v_mfma_f32_16x16x32_bf16 v[52:55], v[16:19], v[56:59], 0
	v_mfma_f32_16x16x32_bf16 v[56:59], v[24:27], v[56:59], 0
	v_mfma_f32_16x16x32_bf16 v[52:55], v[20:23], v[60:63], v[52:55]
	v_mfma_f32_16x16x32_bf16 v[56:59], v[28:31], v[60:63], v[56:59]
	s_barrier
	s_setprio 0
	v_lshl_add_u64 v[176:177], s[24:25], 0, v[136:137]
	s_mov_b64 s[2:3], 0x100
	s_add_i32 s99, s99, s10
	v_lshl_add_u64 v[132:133], v[176:177], 0, s[2:3]
	s_mov_b32 m0, s99
	v_lshl_add_u64 v[178:179], s[24:25], 0, v[140:141]
	s_add_i32 vcc_lo, s99, 0x2000
	ds_read_b128 v[60:63], v151 offset:16384
	ds_read_b128 v[84:87], v151 offset:17408
	ds_read_b128 v[98:101], v151 offset:18432
	ds_read_b128 v[102:105], v151 offset:19456
	ds_read_b128 v[114:117], v151 offset:20480
	ds_read_b128 v[118:121], v151 offset:21504
	ds_read_b128 v[122:125], v151 offset:22528
	ds_read_b128 v[126:129], v151 offset:23552
	global_load_lds_dwordx4 v[132:133], off
	v_lshl_add_u64 v[132:133], v[178:179], 0, s[2:3]
	s_add_u32 s2, s24, 0x40100
	s_mov_b32 m0, vcc_lo
	s_addc_u32 s3, s25, 0
	s_add_i32 vcc_hi, vcc_hi, s10
	global_load_lds_dwordx4 v[132:133], off
	v_lshl_add_u64 v[132:133], s[2:3], 0, v[136:137]
	s_mov_b32 m0, vcc_hi
	s_add_i32 s30, vcc_hi, 0x2000
	global_load_lds_dwordx4 v[132:133], off
	v_lshl_add_u64 v[132:133], s[2:3], 0, v[140:141]
	s_mov_b32 m0, s30
	s_mov_b64 s[34:35], 0x100
	global_load_lds_dwordx4 v[132:133], off
	v_lshl_add_u64 v[132:133], s[28:29], 0, v[134:135]
	s_mov_b32 m0, s22
	s_nop 0
	global_load_lds_dwordx4 v[132:133], off
	v_lshl_add_u64 v[132:133], s[28:29], 0, v[138:139]
	s_mov_b32 m0, s23
	s_nop 0
	global_load_lds_dwordx4 v[132:133], off
	s_waitcnt vmcnt(8)
	s_waitcnt lgkmcnt(0)
	s_setprio 1
	s_barrier
	v_mfma_f32_16x16x32_bf16 v[146:149], v[0:3], v[60:63], 0
	v_mfma_f32_16x16x32_bf16 v[156:159], v[0:3], v[98:101], 0
	v_mfma_f32_16x16x32_bf16 v[164:167], v[0:3], v[114:117], 0
	v_mfma_f32_16x16x32_bf16 v[0:3], v[0:3], v[122:125], 0
	v_mfma_f32_16x16x32_bf16 v[146:149], v[4:7], v[84:87], v[146:149]
	v_mfma_f32_16x16x32_bf16 v[156:159], v[4:7], v[102:105], v[156:159]
	v_mfma_f32_16x16x32_bf16 v[164:167], v[4:7], v[118:121], v[164:167]
	v_mfma_f32_16x16x32_bf16 v[0:3], v[4:7], v[126:129], v[0:3]
	v_mfma_f32_16x16x32_bf16 v[4:7], v[8:11], v[122:125], 0
	v_mfma_f32_16x16x32_bf16 v[152:155], v[8:11], v[60:63], 0
	v_mfma_f32_16x16x32_bf16 v[160:163], v[8:11], v[98:101], 0
	v_mfma_f32_16x16x32_bf16 v[168:171], v[8:11], v[114:117], 0
	v_mfma_f32_16x16x32_bf16 v[8:11], v[12:15], v[126:129], v[4:7]
	v_mfma_f32_16x16x32_bf16 v[152:155], v[12:15], v[84:87], v[152:155]
	v_mfma_f32_16x16x32_bf16 v[160:163], v[12:15], v[102:105], v[160:163]
	v_mfma_f32_16x16x32_bf16 v[168:171], v[12:15], v[118:121], v[168:171]
	s_setprio 0
	s_setprio 1
	v_mfma_f32_16x16x32_bf16 v[4:7], v[16:19], v[60:63], 0
	v_mfma_f32_16x16x32_bf16 v[12:15], v[20:23], v[84:87], v[4:7]
	v_mfma_f32_16x16x32_bf16 v[4:7], v[24:27], v[60:63], 0
	v_mfma_f32_16x16x32_bf16 v[172:175], v[28:31], v[84:87], v[4:7]
	v_mfma_f32_16x16x32_bf16 v[4:7], v[16:19], v[98:101], 0
	v_mfma_f32_16x16x32_bf16 v[180:183], v[20:23], v[102:105], v[4:7]
	v_mfma_f32_16x16x32_bf16 v[4:7], v[24:27], v[98:101], 0
	v_mfma_f32_16x16x32_bf16 v[184:187], v[28:31], v[102:105], v[4:7]
	v_mfma_f32_16x16x32_bf16 v[4:7], v[16:19], v[114:117], 0
	v_mfma_f32_16x16x32_bf16 v[188:191], v[20:23], v[118:121], v[4:7]
	v_mfma_f32_16x16x32_bf16 v[4:7], v[24:27], v[114:117], 0
	v_mfma_f32_16x16x32_bf16 v[192:195], v[28:31], v[118:121], v[4:7]
	v_mfma_f32_16x16x32_bf16 v[4:7], v[16:19], v[122:125], 0
	v_mfma_f32_16x16x32_bf16 v[196:199], v[20:23], v[126:129], v[4:7]
	v_mfma_f32_16x16x32_bf16 v[4:7], v[24:27], v[122:125], 0
	v_mfma_f32_16x16x32_bf16 v[200:203], v[28:31], v[126:129], v[4:7]
	s_barrier
	s_setprio 0
	s_add_i32 s31, 0, 0x18000
	s_add_i32 s13, 0, 0x1c000
	v_add_u32_e32 v132, s31, v97
	v_add_u32_e32 v133, s13, v97
	s_nop 0
	ds_read_b128 v[4:7], v132
	ds_read_b128 v[24:27], v132 offset:1024
	ds_read_b128 v[28:31], v132 offset:2048
	ds_read_b128 v[60:63], v132 offset:3072
	ds_read_b128 v[204:207], v133
	ds_read_b128 v[208:211], v133 offset:1024
	ds_read_b128 v[212:215], v133 offset:2048
	ds_read_b128 v[216:219], v133 offset:3072
	s_add_u32 s2, s42, 0x804000
	s_addc_u32 s3, s43, 0
	s_mov_b32 m0, s39
	v_lshl_add_u64 v[84:85], s[2:3], 0, v[134:135]
	ds_read_b128 v[16:19], v151 offset:32768
	ds_read_b128 v[20:23], v151 offset:33792
	ds_read_b128 v[220:223], v151 offset:34816
	ds_read_b128 v[224:227], v151 offset:35840
	ds_read_b128 v[228:231], v151 offset:36864
	ds_read_b128 v[234:237], v151 offset:37888
	ds_read_b128 v[238:241], v151 offset:38912
	ds_read_b128 v[242:245], v151 offset:39936
	global_load_lds_dwordx4 v[84:85], off
	v_lshl_add_u64 v[84:85], s[2:3], 0, v[138:139]
	s_mov_b32 m0, s56
	s_nop 0
	global_load_lds_dwordx4 v[84:85], off
	s_waitcnt vmcnt(8)
	s_waitcnt lgkmcnt(0)
	s_setprio 1
	s_barrier
	v_mfma_f32_16x16x32_bf16 v[64:67], v[4:7], v[16:19], v[64:67]
	v_mfma_f32_16x16x32_bf16 v[118:121], v[24:27], v[20:23], v[64:67]
	v_mfma_f32_16x16x32_bf16 v[64:67], v[28:31], v[16:19], v[68:71]
	v_mfma_f32_16x16x32_bf16 v[114:117], v[60:63], v[20:23], v[64:67]
	v_mfma_f32_16x16x32_bf16 v[64:67], v[4:7], v[220:223], v[72:75]
	v_mfma_f32_16x16x32_bf16 v[102:105], v[24:27], v[224:227], v[64:67]
	v_mfma_f32_16x16x32_bf16 v[64:67], v[28:31], v[220:223], v[76:79]
	v_mfma_f32_16x16x32_bf16 v[98:101], v[60:63], v[224:227], v[64:67]
	v_mfma_f32_16x16x32_bf16 v[64:67], v[4:7], v[228:231], v[80:83]
	v_mfma_f32_16x16x32_bf16 v[84:87], v[24:27], v[234:237], v[64:67]
	v_mfma_f32_16x16x32_bf16 v[64:67], v[28:31], v[228:231], v[88:91]
	v_mfma_f32_16x16x32_bf16 v[80:83], v[60:63], v[234:237], v[64:67]
	v_mfma_f32_16x16x32_bf16 v[64:67], v[4:7], v[238:241], v[92:95]
	v_mfma_f32_16x16x32_bf16 v[68:71], v[24:27], v[242:245], v[64:67]
	v_mfma_f32_16x16x32_bf16 v[64:67], v[28:31], v[238:241], v[106:109]
	v_mfma_f32_16x16x32_bf16 v[64:67], v[60:63], v[242:245], v[64:67]
	s_setprio 0
	s_setprio 1
	v_mfma_f32_16x16x32_bf16 v[72:75], v[204:207], v[16:19], v[110:113]
	v_mfma_f32_16x16x32_bf16 v[16:19], v[212:215], v[16:19], v[32:35]
	v_mfma_f32_16x16x32_bf16 v[122:125], v[216:219], v[20:23], v[16:19]
	v_mfma_f32_16x16x32_bf16 v[16:19], v[204:207], v[220:223], v[36:39]
	v_mfma_f32_16x16x32_bf16 v[110:113], v[208:211], v[224:227], v[16:19]
	v_mfma_f32_16x16x32_bf16 v[16:19], v[212:215], v[220:223], v[40:43]
	v_mfma_f32_16x16x32_bf16 v[106:109], v[216:219], v[224:227], v[16:19]
	v_mfma_f32_16x16x32_bf16 v[16:19], v[204:207], v[228:231], v[44:47]
	v_mfma_f32_16x16x32_bf16 v[92:95], v[208:211], v[234:237], v[16:19]
	v_mfma_f32_16x16x32_bf16 v[16:19], v[212:215], v[228:231], v[48:51]
	v_mfma_f32_16x16x32_bf16 v[88:91], v[216:219], v[234:237], v[16:19]
	v_mfma_f32_16x16x32_bf16 v[16:19], v[204:207], v[238:241], v[52:55]
	v_mfma_f32_16x16x32_bf16 v[76:79], v[208:211], v[242:245], v[16:19]
	v_mfma_f32_16x16x32_bf16 v[16:19], v[212:215], v[238:241], v[56:59]
	v_mfma_f32_16x16x32_bf16 v[126:129], v[208:211], v[20:23], v[72:75]
	v_mfma_f32_16x16x32_bf16 v[72:75], v[216:219], v[242:245], v[16:19]
	s_barrier
; template <class Epi, class Sched, bool ALIGN_EPI = false, bool SP2 = false>
; __device__ __forceinline__ void gemm_phase(PG8_LAS unsigned char* lds, const Gemm g, const Sched& S, const Epi& E) {
;     ...
;         if constexpr (Epi::PEEL) {
;             const char* a1 = cA + kstepA; const char* a2 = cA + 2 * kstepA; const char* b2 = cB + 2 * kstepB; const char* a3 = a2 + kstepA; const char* b3 = b2 + kstepB;
;             PG8_ITER(8);
;         }
;         for (int t = (Epi::PEEL ? 2 : 0); t < nt; t += 2) {
;             const bool last = (t == nt - 2);
;             const char* a1 = cA + (size_t)(t + 1) * kstepA;
;             const char* a2 = last ? nA : cA + (size_t)(t + 2) * kstepA; const char* b2 = last ? nB : cB + (size_t)(t + 2) * kstepB;
;             const char* a3 = a2 + kstepA; const char* b3 = b2 + kstepB;
;             PG8_ITER(8);
	s_setprio 0
	s_mov_b64 s[2:3], 0x180
	s_add_i32 s31, s31, s10
	s_nop 1
	v_lshl_add_u64 v[16:17], v[176:177], 0, s[2:3]
	s_mov_b32 m0, s31
	s_add_i32 s12, s31, 0x2000
	ds_read_b128 v[40:43], v151 offset:49152
	ds_read_b128 v[44:47], v151 offset:50176
	ds_read_b128 v[220:223], v151 offset:51200
	ds_read_b128 v[224:227], v151 offset:52224
	ds_read_b128 v[228:231], v151 offset:53248
	ds_read_b128 v[234:237], v151 offset:54272
	ds_read_b128 v[238:241], v151 offset:55296
	ds_read_b128 v[242:245], v151 offset:56320
	global_load_lds_dwordx4 v[16:17], off
	v_lshl_add_u64 v[16:17], v[178:179], 0, s[2:3]
	s_add_u32 s2, s24, 0x40180
	s_mov_b32 m0, s12
	s_addc_u32 s3, s25, 0
	s_add_i32 s13, s13, s10
	global_load_lds_dwordx4 v[16:17], off
	v_lshl_add_u64 v[16:17], s[2:3], 0, v[136:137]
	s_mov_b32 m0, s13
	s_add_i32 s11, s13, 0x2000
	global_load_lds_dwordx4 v[16:17], off
	v_lshl_add_u64 v[16:17], s[2:3], 0, v[140:141]
	s_mov_b32 m0, s11
	s_nop 0
	global_load_lds_dwordx4 v[16:17], off
	v_lshl_add_u64 v[16:17], s[44:45], 0, v[134:135]
	s_mov_b32 m0, s59
	s_nop 0
	global_load_lds_dwordx4 v[16:17], off
	v_lshl_add_u64 v[16:17], s[44:45], 0, v[138:139]
	s_mov_b32 m0, s96
	s_nop 0
	global_load_lds_dwordx4 v[16:17], off
	s_waitcnt vmcnt(8)
	s_waitcnt lgkmcnt(0)
	s_setprio 1
	s_barrier
	v_mfma_f32_16x16x32_bf16 v[16:19], v[4:7], v[40:43], v[146:149]
	v_mfma_f32_16x16x32_bf16 v[52:55], v[24:27], v[44:47], v[16:19]
	v_mfma_f32_16x16x32_bf16 v[16:19], v[28:31], v[40:43], v[152:155]
	v_mfma_f32_16x16x32_bf16 v[48:51], v[60:63], v[44:47], v[16:19]
	v_mfma_f32_16x16x32_bf16 v[16:19], v[4:7], v[220:223], v[156:159]
	v_mfma_f32_16x16x32_bf16 v[36:39], v[24:27], v[224:227], v[16:19]
	v_mfma_f32_16x16x32_bf16 v[16:19], v[28:31], v[220:223], v[160:163]
	v_mfma_f32_16x16x32_bf16 v[32:35], v[60:63], v[224:227], v[16:19]
	v_mfma_f32_16x16x32_bf16 v[16:19], v[4:7], v[228:231], v[164:167]
	v_mfma_f32_16x16x32_bf16 v[0:3], v[4:7], v[238:241], v[0:3]
	v_mfma_f32_16x16x32_bf16 v[20:23], v[24:27], v[234:237], v[16:19]
	v_mfma_f32_16x16x32_bf16 v[16:19], v[28:31], v[228:231], v[168:171]
	v_mfma_f32_16x16x32_bf16 v[4:7], v[24:27], v[242:245], v[0:3]
	v_mfma_f32_16x16x32_bf16 v[0:3], v[28:31], v[238:241], v[8:11]
	v_mfma_f32_16x16x32_bf16 v[16:19], v[60:63], v[234:237], v[16:19]
	v_mfma_f32_16x16x32_bf16 v[0:3], v[60:63], v[242:245], v[0:3]
	s_setprio 0
	s_setprio 1
	v_mfma_f32_16x16x32_bf16 v[8:11], v[204:207], v[40:43], v[12:15]
	v_mfma_f32_16x16x32_bf16 v[60:63], v[208:211], v[44:47], v[8:11]
	v_mfma_f32_16x16x32_bf16 v[8:11], v[212:215], v[40:43], v[172:175]
	v_mfma_f32_16x16x32_bf16 v[56:59], v[216:219], v[44:47], v[8:11]
	v_mfma_f32_16x16x32_bf16 v[8:11], v[204:207], v[220:223], v[180:183]
	v_mfma_f32_16x16x32_bf16 v[44:47], v[208:211], v[224:227], v[8:11]
	v_mfma_f32_16x16x32_bf16 v[8:11], v[212:215], v[220:223], v[184:187]
	v_mfma_f32_16x16x32_bf16 v[40:43], v[216:219], v[224:227], v[8:11]
	v_mfma_f32_16x16x32_bf16 v[8:11], v[204:207], v[228:231], v[188:191]
	v_mfma_f32_16x16x32_bf16 v[28:31], v[208:211], v[234:237], v[8:11]
	v_mfma_f32_16x16x32_bf16 v[8:11], v[212:215], v[228:231], v[192:195]
	v_mfma_f32_16x16x32_bf16 v[24:27], v[216:219], v[234:237], v[8:11]
	v_mfma_f32_16x16x32_bf16 v[8:11], v[204:207], v[238:241], v[196:199]
	v_mfma_f32_16x16x32_bf16 v[12:15], v[208:211], v[242:245], v[8:11]
	v_mfma_f32_16x16x32_bf16 v[8:11], v[212:215], v[238:241], v[200:203]
	v_mfma_f32_16x16x32_bf16 v[8:11], v[216:219], v[242:245], v[8:11]
	s_barrier
	s_setprio 0
	s_add_u32 s3, s24, 0x200
	s_addc_u32 s2, s25, 0
	s_add_u32 s24, s42, 0xc04000
	s_addc_u32 s25, s43, 0
	s_mov_b32 s18, 0
.LBB0_250:
	ds_read_b128 v[146:149], v130
	ds_read_b128 v[152:155], v130 offset:1024
	ds_read_b128 v[156:159], v130 offset:2048
	ds_read_b128 v[160:163], v130 offset:3072
	ds_read_b128 v[164:167], v131
	ds_read_b128 v[168:171], v131 offset:1024
	ds_read_b128 v[172:175], v131 offset:2048
	ds_read_b128 v[180:183], v131 offset:3072
	s_add_u32 s16, s24, 0x3fc000
	s_addc_u32 s17, s25, 0
	s_cmp_eq_u32 s18, 12
	s_cselect_b32 s28, s47, s16
	s_cselect_b32 s29, s27, s17
	s_cselect_b32 s44, s54, s3
	s_cselect_b32 s45, s49, s2
	s_add_u32 s42, s28, 0x400000
	s_addc_u32 s43, s29, 0
	s_mov_b32 m0, s55
	v_lshl_add_u64 v[176:177], s[24:25], 0, v[144:145]
	ds_read_b128 v[184:187], v151
	ds_read_b128 v[188:191], v151 offset:1024
	ds_read_b128 v[192:195], v151 offset:2048
	ds_read_b128 v[196:199], v151 offset:3072
	ds_read_b128 v[200:203], v151 offset:4096
	ds_read_b128 v[204:207], v151 offset:5120
	ds_read_b128 v[208:211], v151 offset:6144
	ds_read_b128 v[212:215], v151 offset:7168
	global_load_lds_dwordx4 v[176:177], off
	v_lshl_add_u64 v[176:177], s[24:25], 0, v[142:143]
	s_mov_b32 m0, s98
	s_nop 0
	global_load_lds_dwordx4 v[176:177], off
	s_waitcnt vmcnt(8)
	s_waitcnt lgkmcnt(0)
	s_setprio 1
	s_barrier
	v_mfma_f32_16x16x32_bf16 v[118:121], v[146:149], v[184:187], v[118:121]
	v_mfma_f32_16x16x32_bf16 v[114:117], v[156:159], v[184:187], v[114:117]
	v_mfma_f32_16x16x32_bf16 v[102:105], v[146:149], v[192:195], v[102:105]
	v_mfma_f32_16x16x32_bf16 v[98:101], v[156:159], v[192:195], v[98:101]
	v_mfma_f32_16x16x32_bf16 v[84:87], v[146:149], v[200:203], v[84:87]
	v_mfma_f32_16x16x32_bf16 v[80:83], v[156:159], v[200:203], v[80:83]
	v_mfma_f32_16x16x32_bf16 v[68:71], v[146:149], v[208:211], v[68:71]
	v_mfma_f32_16x16x32_bf16 v[64:67], v[156:159], v[208:211], v[64:67]
	v_mfma_f32_16x16x32_bf16 v[118:121], v[152:155], v[188:191], v[118:121]
	v_mfma_f32_16x16x32_bf16 v[114:117], v[160:163], v[188:191], v[114:117]
	v_mfma_f32_16x16x32_bf16 v[102:105], v[152:155], v[196:199], v[102:105]
	v_mfma_f32_16x16x32_bf16 v[98:101], v[160:163], v[196:199], v[98:101]
	v_mfma_f32_16x16x32_bf16 v[84:87], v[152:155], v[204:207], v[84:87]
	v_mfma_f32_16x16x32_bf16 v[80:83], v[160:163], v[204:207], v[80:83]
	v_mfma_f32_16x16x32_bf16 v[68:71], v[152:155], v[212:215], v[68:71]
	v_mfma_f32_16x16x32_bf16 v[64:67], v[160:163], v[212:215], v[64:67]
	s_setprio 0
	s_setprio 1
	v_mfma_f32_16x16x32_bf16 v[126:129], v[164:167], v[184:187], v[126:129]
	v_mfma_f32_16x16x32_bf16 v[122:125], v[172:175], v[184:187], v[122:125]
	v_mfma_f32_16x16x32_bf16 v[110:113], v[164:167], v[192:195], v[110:113]
	v_mfma_f32_16x16x32_bf16 v[106:109], v[172:175], v[192:195], v[106:109]
	v_mfma_f32_16x16x32_bf16 v[92:95], v[164:167], v[200:203], v[92:95]
	v_mfma_f32_16x16x32_bf16 v[88:91], v[172:175], v[200:203], v[88:91]
	v_mfma_f32_16x16x32_bf16 v[76:79], v[164:167], v[208:211], v[76:79]
	v_mfma_f32_16x16x32_bf16 v[72:75], v[172:175], v[208:211], v[72:75]
	v_mfma_f32_16x16x32_bf16 v[126:129], v[168:171], v[188:191], v[126:129]
	v_mfma_f32_16x16x32_bf16 v[122:125], v[180:183], v[188:191], v[122:125]
	v_mfma_f32_16x16x32_bf16 v[110:113], v[168:171], v[196:199], v[110:113]
	v_mfma_f32_16x16x32_bf16 v[106:109], v[180:183], v[196:199], v[106:109]
	v_mfma_f32_16x16x32_bf16 v[92:95], v[168:171], v[204:207], v[92:95]
	v_mfma_f32_16x16x32_bf16 v[88:91], v[180:183], v[204:207], v[88:91]
	v_mfma_f32_16x16x32_bf16 v[76:79], v[168:171], v[212:215], v[76:79]
	v_mfma_f32_16x16x32_bf16 v[72:75], v[180:183], v[212:215], v[72:75]
	s_barrier
	s_setprio 0
	s_mov_b32 m0, s99
	v_lshl_add_u64 v[176:177], s[44:45], 0, v[136:137]
	s_add_u32 s16, s44, 0x40000
	ds_read_b128 v[184:187], v151 offset:16384
	ds_read_b128 v[188:191], v151 offset:17408
	ds_read_b128 v[192:195], v151 offset:18432
	ds_read_b128 v[196:199], v151 offset:19456
	ds_read_b128 v[200:203], v151 offset:20480
	ds_read_b128 v[204:207], v151 offset:21504
	ds_read_b128 v[208:211], v151 offset:22528
	ds_read_b128 v[212:215], v151 offset:23552
	global_load_lds_dwordx4 v[176:177], off
	v_lshl_add_u64 v[178:179], s[44:45], 0, v[140:141]
	s_mov_b32 m0, vcc_lo
	s_addc_u32 s17, s45, 0
	global_load_lds_dwordx4 v[178:179], off
	v_lshl_add_u64 v[216:217], s[16:17], 0, v[136:137]
	s_mov_b32 m0, vcc_hi
	s_nop 0
	global_load_lds_dwordx4 v[216:217], off
	v_lshl_add_u64 v[216:217], s[16:17], 0, v[140:141]
	s_mov_b32 m0, s30
	s_nop 0
	global_load_lds_dwordx4 v[216:217], off
	v_lshl_add_u64 v[216:217], s[28:29], 0, v[134:135]
	s_mov_b32 m0, s22
	s_nop 0
	global_load_lds_dwordx4 v[216:217], off
	v_lshl_add_u64 v[216:217], s[28:29], 0, v[138:139]
	s_mov_b32 m0, s23
	s_nop 0
	global_load_lds_dwordx4 v[216:217], off
	s_waitcnt vmcnt(8)
	s_waitcnt lgkmcnt(0)
	s_setprio 1
	s_barrier
	v_mfma_f32_16x16x32_bf16 v[52:55], v[146:149], v[184:187], v[52:55]
	v_mfma_f32_16x16x32_bf16 v[48:51], v[156:159], v[184:187], v[48:51]
	v_mfma_f32_16x16x32_bf16 v[36:39], v[146:149], v[192:195], v[36:39]
	v_mfma_f32_16x16x32_bf16 v[32:35], v[156:159], v[192:195], v[32:35]
	v_mfma_f32_16x16x32_bf16 v[20:23], v[146:149], v[200:203], v[20:23]
	v_mfma_f32_16x16x32_bf16 v[16:19], v[156:159], v[200:203], v[16:19]
	v_mfma_f32_16x16x32_bf16 v[4:7], v[146:149], v[208:211], v[4:7]
	v_mfma_f32_16x16x32_bf16 v[0:3], v[156:159], v[208:211], v[0:3]
	v_mfma_f32_16x16x32_bf16 v[52:55], v[152:155], v[188:191], v[52:55]
	v_mfma_f32_16x16x32_bf16 v[48:51], v[160:163], v[188:191], v[48:51]
	v_mfma_f32_16x16x32_bf16 v[36:39], v[152:155], v[196:199], v[36:39]
	v_mfma_f32_16x16x32_bf16 v[32:35], v[160:163], v[196:199], v[32:35]
	v_mfma_f32_16x16x32_bf16 v[20:23], v[152:155], v[204:207], v[20:23]
	v_mfma_f32_16x16x32_bf16 v[16:19], v[160:163], v[204:207], v[16:19]
	v_mfma_f32_16x16x32_bf16 v[4:7], v[152:155], v[212:215], v[4:7]
	v_mfma_f32_16x16x32_bf16 v[0:3], v[160:163], v[212:215], v[0:3]
	s_setprio 0
	s_setprio 1
	v_mfma_f32_16x16x32_bf16 v[60:63], v[164:167], v[184:187], v[60:63]
	v_mfma_f32_16x16x32_bf16 v[56:59], v[172:175], v[184:187], v[56:59]
	v_mfma_f32_16x16x32_bf16 v[44:47], v[164:167], v[192:195], v[44:47]
	v_mfma_f32_16x16x32_bf16 v[40:43], v[172:175], v[192:195], v[40:43]
	v_mfma_f32_16x16x32_bf16 v[28:31], v[164:167], v[200:203], v[28:31]
	v_mfma_f32_16x16x32_bf16 v[24:27], v[172:175], v[200:203], v[24:27]
	v_mfma_f32_16x16x32_bf16 v[12:15], v[164:167], v[208:211], v[12:15]
	v_mfma_f32_16x16x32_bf16 v[8:11], v[172:175], v[208:211], v[8:11]
	v_mfma_f32_16x16x32_bf16 v[60:63], v[168:171], v[188:191], v[60:63]
	v_mfma_f32_16x16x32_bf16 v[56:59], v[180:183], v[188:191], v[56:59]
	v_mfma_f32_16x16x32_bf16 v[44:47], v[168:171], v[196:199], v[44:47]
	v_mfma_f32_16x16x32_bf16 v[40:43], v[180:183], v[196:199], v[40:43]
	v_mfma_f32_16x16x32_bf16 v[28:31], v[168:171], v[204:207], v[28:31]
	v_mfma_f32_16x16x32_bf16 v[24:27], v[180:183], v[204:207], v[24:27]
	v_mfma_f32_16x16x32_bf16 v[12:15], v[168:171], v[212:215], v[12:15]
	v_mfma_f32_16x16x32_bf16 v[8:11], v[180:183], v[212:215], v[8:11]
	s_barrier
	s_setprio 0
	ds_read_b128 v[146:149], v132
	ds_read_b128 v[152:155], v132 offset:1024
	ds_read_b128 v[156:159], v132 offset:2048
	ds_read_b128 v[160:163], v132 offset:3072
	ds_read_b128 v[164:167], v133
	ds_read_b128 v[168:171], v133 offset:1024
	ds_read_b128 v[172:175], v133 offset:2048
	ds_read_b128 v[180:183], v133 offset:3072
	s_add_u32 s16, s28, 0x4000
	s_addc_u32 s17, s29, 0
	s_mov_b32 m0, s39
	v_lshl_add_u64 v[216:217], s[16:17], 0, v[134:135]
	ds_read_b128 v[184:187], v151 offset:32768
	ds_read_b128 v[188:191], v151 offset:33792
	ds_read_b128 v[192:195], v151 offset:34816
	ds_read_b128 v[196:199], v151 offset:35840
	ds_read_b128 v[200:203], v151 offset:36864
	ds_read_b128 v[204:207], v151 offset:37888
	ds_read_b128 v[208:211], v151 offset:38912
	ds_read_b128 v[212:215], v151 offset:39936
	global_load_lds_dwordx4 v[216:217], off
	v_lshl_add_u64 v[216:217], s[16:17], 0, v[138:139]
	s_mov_b32 m0, s56
	s_nop 0
	global_load_lds_dwordx4 v[216:217], off
	s_waitcnt vmcnt(8)
	s_waitcnt lgkmcnt(0)
	s_setprio 1
	s_barrier
	v_mfma_f32_16x16x32_bf16 v[118:121], v[146:149], v[184:187], v[118:121]
	v_mfma_f32_16x16x32_bf16 v[114:117], v[156:159], v[184:187], v[114:117]
	v_mfma_f32_16x16x32_bf16 v[102:105], v[146:149], v[192:195], v[102:105]
	v_mfma_f32_16x16x32_bf16 v[98:101], v[156:159], v[192:195], v[98:101]
	v_mfma_f32_16x16x32_bf16 v[84:87], v[146:149], v[200:203], v[84:87]
	v_mfma_f32_16x16x32_bf16 v[80:83], v[156:159], v[200:203], v[80:83]
	v_mfma_f32_16x16x32_bf16 v[68:71], v[146:149], v[208:211], v[68:71]
	v_mfma_f32_16x16x32_bf16 v[64:67], v[156:159], v[208:211], v[64:67]
	v_mfma_f32_16x16x32_bf16 v[118:121], v[152:155], v[188:191], v[118:121]
	v_mfma_f32_16x16x32_bf16 v[114:117], v[160:163], v[188:191], v[114:117]
	v_mfma_f32_16x16x32_bf16 v[102:105], v[152:155], v[196:199], v[102:105]
	v_mfma_f32_16x16x32_bf16 v[98:101], v[160:163], v[196:199], v[98:101]
	v_mfma_f32_16x16x32_bf16 v[84:87], v[152:155], v[204:207], v[84:87]
	v_mfma_f32_16x16x32_bf16 v[80:83], v[160:163], v[204:207], v[80:83]
	v_mfma_f32_16x16x32_bf16 v[68:71], v[152:155], v[212:215], v[68:71]
	v_mfma_f32_16x16x32_bf16 v[64:67], v[160:163], v[212:215], v[64:67]
	s_setprio 0
	s_setprio 1
	v_mfma_f32_16x16x32_bf16 v[126:129], v[164:167], v[184:187], v[126:129]
	v_mfma_f32_16x16x32_bf16 v[122:125], v[172:175], v[184:187], v[122:125]
	v_mfma_f32_16x16x32_bf16 v[110:113], v[164:167], v[192:195], v[110:113]
	v_mfma_f32_16x16x32_bf16 v[106:109], v[172:175], v[192:195], v[106:109]
	v_mfma_f32_16x16x32_bf16 v[92:95], v[164:167], v[200:203], v[92:95]
	v_mfma_f32_16x16x32_bf16 v[88:91], v[172:175], v[200:203], v[88:91]
	v_mfma_f32_16x16x32_bf16 v[76:79], v[164:167], v[208:211], v[76:79]
	v_mfma_f32_16x16x32_bf16 v[72:75], v[172:175], v[208:211], v[72:75]
	v_mfma_f32_16x16x32_bf16 v[126:129], v[168:171], v[188:191], v[126:129]
	v_mfma_f32_16x16x32_bf16 v[122:125], v[180:183], v[188:191], v[122:125]
	v_mfma_f32_16x16x32_bf16 v[110:113], v[168:171], v[196:199], v[110:113]
	v_mfma_f32_16x16x32_bf16 v[106:109], v[180:183], v[196:199], v[106:109]
	v_mfma_f32_16x16x32_bf16 v[92:95], v[168:171], v[204:207], v[92:95]
	v_mfma_f32_16x16x32_bf16 v[88:91], v[180:183], v[204:207], v[88:91]
	v_mfma_f32_16x16x32_bf16 v[76:79], v[168:171], v[212:215], v[76:79]
	v_mfma_f32_16x16x32_bf16 v[72:75], v[180:183], v[212:215], v[72:75]
	s_barrier
; template <class Epi, class Sched, bool ALIGN_EPI = false, bool SP2 = false>
; __device__ __forceinline__ void gemm_phase(PG8_LAS unsigned char* lds, const Gemm g, const Sched& S, const Epi& E) {
;     ...
;         if constexpr (Epi::PEEL) {
;             const char* a1 = cA + kstepA; const char* a2 = cA + 2 * kstepA; const char* b2 = cB + 2 * kstepB; const char* a3 = a2 + kstepA; const char* b3 = b2 + kstepB;
;             PG8_ITER(8);
;         }
;         for (int t = (Epi::PEEL ? 2 : 0); t < nt; t += 2) {
;             const bool last = (t == nt - 2);
;             const char* a1 = cA + (size_t)(t + 1) * kstepA;
;             const char* a2 = last ? nA : cA + (size_t)(t + 2) * kstepA; const char* b2 = last ? nB : cB + (size_t)(t + 2) * kstepB;
;             const char* a3 = a2 + kstepA; const char* b3 = b2 + kstepB;
;             PG8_ITER(8);
;         }
	s_setprio 0
	s_mov_b32 m0, s31
	v_lshl_add_u64 v[176:177], v[176:177], 0, s[36:37]
	s_add_u32 s16, s44, 0x40080
	ds_read_b128 v[184:187], v151 offset:49152
	ds_read_b128 v[188:191], v151 offset:50176
	ds_read_b128 v[192:195], v151 offset:51200
	ds_read_b128 v[196:199], v151 offset:52224
	ds_read_b128 v[200:203], v151 offset:53248
	ds_read_b128 v[204:207], v151 offset:54272
	ds_read_b128 v[208:211], v151 offset:55296
	ds_read_b128 v[212:215], v151 offset:56320
	global_load_lds_dwordx4 v[176:177], off
	v_lshl_add_u64 v[176:177], v[178:179], 0, s[36:37]
	s_mov_b32 m0, s12
	s_addc_u32 s17, s45, 0
	global_load_lds_dwordx4 v[176:177], off
	v_lshl_add_u64 v[176:177], s[16:17], 0, v[136:137]
	s_mov_b32 m0, s13
	s_nop 0
	global_load_lds_dwordx4 v[176:177], off
	v_lshl_add_u64 v[176:177], s[16:17], 0, v[140:141]
	s_mov_b32 m0, s11
	s_nop 0
	global_load_lds_dwordx4 v[176:177], off
	v_lshl_add_u64 v[176:177], s[42:43], 0, v[134:135]
	s_mov_b32 m0, s59
	s_nop 0
	global_load_lds_dwordx4 v[176:177], off
	v_lshl_add_u64 v[176:177], s[42:43], 0, v[138:139]
	s_mov_b32 m0, s96
	s_nop 0
	global_load_lds_dwordx4 v[176:177], off
	s_waitcnt vmcnt(8)
	s_waitcnt lgkmcnt(0)
	s_setprio 1
	s_barrier
	v_mfma_f32_16x16x32_bf16 v[52:55], v[146:149], v[184:187], v[52:55]
	v_mfma_f32_16x16x32_bf16 v[48:51], v[156:159], v[184:187], v[48:51]
	v_mfma_f32_16x16x32_bf16 v[36:39], v[146:149], v[192:195], v[36:39]
	v_mfma_f32_16x16x32_bf16 v[32:35], v[156:159], v[192:195], v[32:35]
	v_mfma_f32_16x16x32_bf16 v[20:23], v[146:149], v[200:203], v[20:23]
	v_mfma_f32_16x16x32_bf16 v[16:19], v[156:159], v[200:203], v[16:19]
	v_mfma_f32_16x16x32_bf16 v[4:7], v[146:149], v[208:211], v[4:7]
	v_mfma_f32_16x16x32_bf16 v[0:3], v[156:159], v[208:211], v[0:3]
	v_mfma_f32_16x16x32_bf16 v[52:55], v[152:155], v[188:191], v[52:55]
	v_mfma_f32_16x16x32_bf16 v[48:51], v[160:163], v[188:191], v[48:51]
	v_mfma_f32_16x16x32_bf16 v[36:39], v[152:155], v[196:199], v[36:39]
	v_mfma_f32_16x16x32_bf16 v[32:35], v[160:163], v[196:199], v[32:35]
	v_mfma_f32_16x16x32_bf16 v[20:23], v[152:155], v[204:207], v[20:23]
	v_mfma_f32_16x16x32_bf16 v[16:19], v[160:163], v[204:207], v[16:19]
	v_mfma_f32_16x16x32_bf16 v[4:7], v[152:155], v[212:215], v[4:7]
	v_mfma_f32_16x16x32_bf16 v[0:3], v[160:163], v[212:215], v[0:3]
	s_setprio 0
	s_setprio 1
	v_mfma_f32_16x16x32_bf16 v[60:63], v[164:167], v[184:187], v[60:63]
	v_mfma_f32_16x16x32_bf16 v[56:59], v[172:175], v[184:187], v[56:59]
	v_mfma_f32_16x16x32_bf16 v[44:47], v[164:167], v[192:195], v[44:47]
	v_mfma_f32_16x16x32_bf16 v[40:43], v[172:175], v[192:195], v[40:43]
	v_mfma_f32_16x16x32_bf16 v[28:31], v[164:167], v[200:203], v[28:31]
	v_mfma_f32_16x16x32_bf16 v[24:27], v[172:175], v[200:203], v[24:27]
	v_mfma_f32_16x16x32_bf16 v[12:15], v[164:167], v[208:211], v[12:15]
	v_mfma_f32_16x16x32_bf16 v[8:11], v[172:175], v[208:211], v[8:11]
	v_mfma_f32_16x16x32_bf16 v[60:63], v[168:171], v[188:191], v[60:63]
	v_mfma_f32_16x16x32_bf16 v[56:59], v[180:183], v[188:191], v[56:59]
	v_mfma_f32_16x16x32_bf16 v[44:47], v[168:171], v[196:199], v[44:47]
	v_mfma_f32_16x16x32_bf16 v[40:43], v[180:183], v[196:199], v[40:43]
	v_mfma_f32_16x16x32_bf16 v[28:31], v[168:171], v[204:207], v[28:31]
	v_mfma_f32_16x16x32_bf16 v[24:27], v[180:183], v[204:207], v[24:27]
	v_mfma_f32_16x16x32_bf16 v[12:15], v[168:171], v[212:215], v[12:15]
	v_mfma_f32_16x16x32_bf16 v[8:11], v[180:183], v[212:215], v[8:11]
	s_barrier
	s_setprio 0
	s_add_i32 s18, s18, 2
	s_add_u32 s3, s3, 0x100
	s_addc_u32 s2, s2, 0
	s_add_u32 s24, s24, 0x800000
	s_addc_u32 s25, s25, 0
	s_cmp_gt_u32 s18, 13
	s_cbranch_scc0 .LBB0_250
	v_readlane_b32 s2, v255, 33
	v_readlane_b32 s3, v255, 34
	v_readlane_b32 s12, v255, 31
	s_and_b64 vcc, exec, s[2:3]
	v_readlane_b32 s13, v255, 32
	s_cbranch_vccz .LBB0_253
	s_barrier

; template <class Epi, class Sched, bool ALIGN_EPI = false, bool SP2 = false>
; __device__ __forceinline__ void gemm_phase(PG8_LAS unsigned char* lds, const Gemm g, const Sched& S, const Epi& E) {
;     ...
;         if constexpr (Epi::PEEL) {
;             const char* a1 = cA + kstepA; const char* a2 = cA + 2 * kstepA; const char* b2 = cB + 2 * kstepB; const char* a3 = a2 + kstepA; const char* b3 = b2 + kstepB;
;             PG8_ITER(8);
;         }
;         for (int t = (Epi::PEEL ? 2 : 0); t < nt; t += 2) {
;             const bool last = (t == nt - 2);
;             const char* a1 = cA + (size_t)(t + 1) * kstepA;
;             const char* a2 = last ? nA : cA + (size_t)(t + 2) * kstepA; const char* b2 = last ? nB : cB + (size_t)(t + 2) * kstepB;
;             const char* a3 = a2 + kstepA; const char* b3 = b2 + kstepB;
;             PG8_ITER(8);
.LBB0_345:
	s_add_i32 s10, s10, 2
	s_add_u32 s44, s42, s34
	s_addc_u32 s45, s43, s35
	s_add_i32 s18, 0, 0x10000
	s_and_b64 s[2:3], exec, s[46:47]
	s_cselect_b32 s3, s13, s59
	s_cselect_b32 s2, s12, s58
	s_add_i32 s38, 0, 0x14000
	v_add_u32_e32 v142, s18, v97
	v_add_u32_e32 v170, s38, v97
	ds_read_b128 v[122:125], v142
	ds_read_b128 v[126:129], v142 offset:1024
	ds_read_b128 v[138:141], v142 offset:2048
	ds_read_b128 v[142:145], v142 offset:3072
	ds_read_b128 v[146:149], v170
	ds_read_b128 v[150:153], v170 offset:1024
	ds_read_b128 v[154:157], v170 offset:2048
	ds_read_b128 v[170:173], v170 offset:3072
	v_lshl_add_u64 v[178:179], s[24:25], 0, v[168:169]
	s_add_i32 m0, s97, 0xc000
	ds_read_b128 v[174:177], v188
	ds_read_b128 v[180:183], v188 offset:1024
	ds_read_b128 v[184:187], v188 offset:2048
	ds_read_b128 v[190:193], v188 offset:3072
	ds_read_b128 v[194:197], v188 offset:4096
	ds_read_b128 v[198:201], v188 offset:5120
	ds_read_b128 v[202:205], v188 offset:6144
	ds_read_b128 v[206:209], v188 offset:7168
	global_load_lds_dwordx4 v[178:179], off
	v_lshl_add_u64 v[178:179], s[24:25], 0, v[166:167]
	s_add_i32 m0, s97, 0xe000
	s_nop 0
	global_load_lds_dwordx4 v[178:179], off
	s_waitcnt vmcnt(8)
	s_waitcnt lgkmcnt(0)
	s_setprio 1
	s_barrier
	v_mfma_f32_16x16x32_bf16 v[134:137], v[122:125], v[174:177], v[134:137]
	v_mfma_f32_16x16x32_bf16 v[130:133], v[138:141], v[174:177], v[130:133]
	v_mfma_f32_16x16x32_bf16 v[110:113], v[122:125], v[184:187], v[110:113]
	v_mfma_f32_16x16x32_bf16 v[106:109], v[138:141], v[184:187], v[106:109]
	v_mfma_f32_16x16x32_bf16 v[92:95], v[122:125], v[194:197], v[92:95]
	v_mfma_f32_16x16x32_bf16 v[88:91], v[138:141], v[194:197], v[88:91]
	v_mfma_f32_16x16x32_bf16 v[76:79], v[122:125], v[202:205], v[76:79]
	v_mfma_f32_16x16x32_bf16 v[72:75], v[138:141], v[202:205], v[72:75]
	v_mfma_f32_16x16x32_bf16 v[134:137], v[126:129], v[180:183], v[134:137]
	v_mfma_f32_16x16x32_bf16 v[130:133], v[142:145], v[180:183], v[130:133]
	v_mfma_f32_16x16x32_bf16 v[110:113], v[126:129], v[190:193], v[110:113]
	v_mfma_f32_16x16x32_bf16 v[106:109], v[142:145], v[190:193], v[106:109]
	v_mfma_f32_16x16x32_bf16 v[92:95], v[126:129], v[198:201], v[92:95]
	v_mfma_f32_16x16x32_bf16 v[88:91], v[142:145], v[198:201], v[88:91]
	v_mfma_f32_16x16x32_bf16 v[76:79], v[126:129], v[206:209], v[76:79]
	v_mfma_f32_16x16x32_bf16 v[72:75], v[142:145], v[206:209], v[72:75]
	s_setprio 0
	s_setprio 1
	v_mfma_f32_16x16x32_bf16 v[118:121], v[146:149], v[174:177], v[118:121]
	v_mfma_f32_16x16x32_bf16 v[114:117], v[154:157], v[174:177], v[114:117]
	v_mfma_f32_16x16x32_bf16 v[102:105], v[146:149], v[184:187], v[102:105]
	v_mfma_f32_16x16x32_bf16 v[98:101], v[154:157], v[184:187], v[98:101]
	v_mfma_f32_16x16x32_bf16 v[84:87], v[146:149], v[194:197], v[84:87]
	v_mfma_f32_16x16x32_bf16 v[80:83], v[154:157], v[194:197], v[80:83]
	v_mfma_f32_16x16x32_bf16 v[68:71], v[146:149], v[202:205], v[68:71]
	v_mfma_f32_16x16x32_bf16 v[64:67], v[154:157], v[202:205], v[64:67]
	v_mfma_f32_16x16x32_bf16 v[118:121], v[150:153], v[180:183], v[118:121]
	v_mfma_f32_16x16x32_bf16 v[114:117], v[170:173], v[180:183], v[114:117]
	v_mfma_f32_16x16x32_bf16 v[102:105], v[150:153], v[190:193], v[102:105]
	v_mfma_f32_16x16x32_bf16 v[98:101], v[170:173], v[190:193], v[98:101]
	v_mfma_f32_16x16x32_bf16 v[84:87], v[150:153], v[198:201], v[84:87]
	v_mfma_f32_16x16x32_bf16 v[80:83], v[170:173], v[198:201], v[80:83]
	v_mfma_f32_16x16x32_bf16 v[68:71], v[150:153], v[206:209], v[68:71]
	v_mfma_f32_16x16x32_bf16 v[64:67], v[170:173], v[206:209], v[64:67]
	s_barrier
	s_setprio 0
	s_add_i32 s18, s18, s96
	v_lshl_add_u64 v[178:179], s[2:3], 0, v[162:163]
	s_mov_b32 m0, s18
	ds_read_b128 v[174:177], v188 offset:16384
	ds_read_b128 v[180:183], v188 offset:17408
	ds_read_b128 v[184:187], v188 offset:18432
	ds_read_b128 v[190:193], v188 offset:19456
	ds_read_b128 v[194:197], v188 offset:20480
	ds_read_b128 v[198:201], v188 offset:21504
	ds_read_b128 v[202:205], v188 offset:22528
	ds_read_b128 v[206:209], v188 offset:23552
	global_load_lds_dwordx4 v[178:179], off
	s_add_i32 m0, s18, 0x2000
	v_lshl_add_u64 v[210:211], s[2:3], 0, v[158:159]
	s_add_u32 s2, s2, s48
	s_addc_u32 s3, s3, 0
	s_add_i32 s18, s38, s96
	global_load_lds_dwordx4 v[210:211], off
	v_lshl_add_u64 v[212:213], s[2:3], 0, v[162:163]
	s_mov_b32 m0, s18
	v_lshl_add_u64 v[214:215], s[2:3], 0, v[158:159]
	global_load_lds_dwordx4 v[212:213], off
	s_add_i32 m0, s18, 0x2000
	v_lshl_add_u64 v[216:217], s[42:43], 0, v[164:165]
	global_load_lds_dwordx4 v[214:215], off
	s_mov_b32 m0, s97
	s_nop 0
	global_load_lds_dwordx4 v[216:217], off
	v_lshl_add_u64 v[216:217], s[42:43], 0, v[160:161]
	s_mov_b32 m0, s22
	s_nop 0
	global_load_lds_dwordx4 v[216:217], off
	s_waitcnt vmcnt(8)
	s_waitcnt lgkmcnt(0)
	s_setprio 1
	s_barrier
	v_mfma_f32_16x16x32_bf16 v[60:63], v[122:125], v[174:177], v[60:63]
	v_mfma_f32_16x16x32_bf16 v[56:59], v[138:141], v[174:177], v[56:59]
	v_mfma_f32_16x16x32_bf16 v[44:47], v[122:125], v[184:187], v[44:47]
	v_mfma_f32_16x16x32_bf16 v[40:43], v[138:141], v[184:187], v[40:43]
	v_mfma_f32_16x16x32_bf16 v[28:31], v[122:125], v[194:197], v[28:31]
	v_mfma_f32_16x16x32_bf16 v[24:27], v[138:141], v[194:197], v[24:27]
	v_mfma_f32_16x16x32_bf16 v[12:15], v[122:125], v[202:205], v[12:15]
	v_mfma_f32_16x16x32_bf16 v[8:11], v[138:141], v[202:205], v[8:11]
	v_mfma_f32_16x16x32_bf16 v[60:63], v[126:129], v[180:183], v[60:63]
	v_mfma_f32_16x16x32_bf16 v[56:59], v[142:145], v[180:183], v[56:59]
	v_mfma_f32_16x16x32_bf16 v[44:47], v[126:129], v[190:193], v[44:47]
	v_mfma_f32_16x16x32_bf16 v[40:43], v[142:145], v[190:193], v[40:43]
	v_mfma_f32_16x16x32_bf16 v[28:31], v[126:129], v[198:201], v[28:31]
	v_mfma_f32_16x16x32_bf16 v[24:27], v[142:145], v[198:201], v[24:27]
	v_mfma_f32_16x16x32_bf16 v[12:15], v[126:129], v[206:209], v[12:15]
	v_mfma_f32_16x16x32_bf16 v[8:11], v[142:145], v[206:209], v[8:11]
	s_setprio 0
	s_setprio 1
	v_mfma_f32_16x16x32_bf16 v[52:55], v[146:149], v[174:177], v[52:55]
	v_mfma_f32_16x16x32_bf16 v[48:51], v[154:157], v[174:177], v[48:51]
	v_mfma_f32_16x16x32_bf16 v[36:39], v[146:149], v[184:187], v[36:39]
	v_mfma_f32_16x16x32_bf16 v[32:35], v[154:157], v[184:187], v[32:35]
	v_mfma_f32_16x16x32_bf16 v[20:23], v[146:149], v[194:197], v[20:23]
	v_mfma_f32_16x16x32_bf16 v[16:19], v[154:157], v[194:197], v[16:19]
	v_mfma_f32_16x16x32_bf16 v[4:7], v[146:149], v[202:205], v[4:7]
	v_mfma_f32_16x16x32_bf16 v[0:3], v[154:157], v[202:205], v[0:3]
	v_mfma_f32_16x16x32_bf16 v[52:55], v[150:153], v[180:183], v[52:55]
	v_mfma_f32_16x16x32_bf16 v[48:51], v[170:173], v[180:183], v[48:51]
	v_mfma_f32_16x16x32_bf16 v[36:39], v[150:153], v[190:193], v[36:39]
	v_mfma_f32_16x16x32_bf16 v[32:35], v[170:173], v[190:193], v[32:35]
	v_mfma_f32_16x16x32_bf16 v[20:23], v[150:153], v[198:201], v[20:23]
	v_mfma_f32_16x16x32_bf16 v[16:19], v[170:173], v[198:201], v[16:19]
	v_mfma_f32_16x16x32_bf16 v[4:7], v[150:153], v[206:209], v[4:7]
	v_mfma_f32_16x16x32_bf16 v[0:3], v[170:173], v[206:209], v[0:3]
	s_barrier
	s_setprio 0
	s_add_i32 s18, 0, 0x18000
	s_add_i32 s38, 0, 0x1c000
	v_add_u32_e32 v142, s18, v97
	v_add_u32_e32 v170, s38, v97
	ds_read_b128 v[122:125], v142
	ds_read_b128 v[126:129], v142 offset:1024
	ds_read_b128 v[138:141], v142 offset:2048
	ds_read_b128 v[142:145], v142 offset:3072
	ds_read_b128 v[146:149], v170
	ds_read_b128 v[150:153], v170 offset:1024
	ds_read_b128 v[154:157], v170 offset:2048
	ds_read_b128 v[170:173], v170 offset:3072
	s_add_u32 s2, s42, s98
	s_addc_u32 s3, s43, 0
	s_mov_b32 m0, s23
	v_lshl_add_u64 v[216:217], s[2:3], 0, v[164:165]
	ds_read_b128 v[174:177], v188 offset:32768
	ds_read_b128 v[180:183], v188 offset:33792
	ds_read_b128 v[184:187], v188 offset:34816
	ds_read_b128 v[190:193], v188 offset:35840
	ds_read_b128 v[194:197], v188 offset:36864
	ds_read_b128 v[198:201], v188 offset:37888
	ds_read_b128 v[202:205], v188 offset:38912
	ds_read_b128 v[206:209], v188 offset:39936
	global_load_lds_dwordx4 v[216:217], off
	v_lshl_add_u64 v[216:217], s[2:3], 0, v[160:161]
	s_mov_b32 m0, s19
	s_nop 0
	global_load_lds_dwordx4 v[216:217], off
	s_waitcnt vmcnt(8)
	s_waitcnt lgkmcnt(0)
	s_setprio 1
	s_barrier
	v_mfma_f32_16x16x32_bf16 v[134:137], v[122:125], v[174:177], v[134:137]
	v_mfma_f32_16x16x32_bf16 v[130:133], v[138:141], v[174:177], v[130:133]
	v_mfma_f32_16x16x32_bf16 v[110:113], v[122:125], v[184:187], v[110:113]
	v_mfma_f32_16x16x32_bf16 v[106:109], v[138:141], v[184:187], v[106:109]
	v_mfma_f32_16x16x32_bf16 v[92:95], v[122:125], v[194:197], v[92:95]
	v_mfma_f32_16x16x32_bf16 v[88:91], v[138:141], v[194:197], v[88:91]
	v_mfma_f32_16x16x32_bf16 v[76:79], v[122:125], v[202:205], v[76:79]
	v_mfma_f32_16x16x32_bf16 v[72:75], v[138:141], v[202:205], v[72:75]
	v_mfma_f32_16x16x32_bf16 v[134:137], v[126:129], v[180:183], v[134:137]
	v_mfma_f32_16x16x32_bf16 v[130:133], v[142:145], v[180:183], v[130:133]
	v_mfma_f32_16x16x32_bf16 v[110:113], v[126:129], v[190:193], v[110:113]
	v_mfma_f32_16x16x32_bf16 v[106:109], v[142:145], v[190:193], v[106:109]
	v_mfma_f32_16x16x32_bf16 v[92:95], v[126:129], v[198:201], v[92:95]
	v_mfma_f32_16x16x32_bf16 v[88:91], v[142:145], v[198:201], v[88:91]
	v_mfma_f32_16x16x32_bf16 v[76:79], v[126:129], v[206:209], v[76:79]
	v_mfma_f32_16x16x32_bf16 v[72:75], v[142:145], v[206:209], v[72:75]
	s_setprio 0
	s_setprio 1
	v_mfma_f32_16x16x32_bf16 v[118:121], v[146:149], v[174:177], v[118:121]
	v_mfma_f32_16x16x32_bf16 v[114:117], v[154:157], v[174:177], v[114:117]
	v_mfma_f32_16x16x32_bf16 v[102:105], v[146:149], v[184:187], v[102:105]
	v_mfma_f32_16x16x32_bf16 v[98:101], v[154:157], v[184:187], v[98:101]
	v_mfma_f32_16x16x32_bf16 v[84:87], v[146:149], v[194:197], v[84:87]
	v_mfma_f32_16x16x32_bf16 v[80:83], v[154:157], v[194:197], v[80:83]
	v_mfma_f32_16x16x32_bf16 v[68:71], v[146:149], v[202:205], v[68:71]
	v_mfma_f32_16x16x32_bf16 v[64:67], v[154:157], v[202:205], v[64:67]
	v_mfma_f32_16x16x32_bf16 v[118:121], v[150:153], v[180:183], v[118:121]
	v_mfma_f32_16x16x32_bf16 v[114:117], v[170:173], v[180:183], v[114:117]
	v_mfma_f32_16x16x32_bf16 v[102:105], v[150:153], v[190:193], v[102:105]
	v_mfma_f32_16x16x32_bf16 v[98:101], v[170:173], v[190:193], v[98:101]
	v_mfma_f32_16x16x32_bf16 v[84:87], v[150:153], v[198:201], v[84:87]
	v_mfma_f32_16x16x32_bf16 v[80:83], v[170:173], v[198:201], v[80:83]
	v_mfma_f32_16x16x32_bf16 v[68:71], v[150:153], v[206:209], v[68:71]
	v_mfma_f32_16x16x32_bf16 v[64:67], v[170:173], v[206:209], v[64:67]
	s_barrier
; template <class Epi, class Sched, bool ALIGN_EPI = false, bool SP2 = false>
; __device__ __forceinline__ void gemm_phase(PG8_LAS unsigned char* lds, const Gemm g, const Sched& S, const Epi& E) {
;     ...
;         if constexpr (Epi::PEEL) {
;             const char* a1 = cA + kstepA; const char* a2 = cA + 2 * kstepA; const char* b2 = cB + 2 * kstepB; const char* a3 = a2 + kstepA; const char* b3 = b2 + kstepB;
;             PG8_ITER(8);
;         }
;         for (int t = (Epi::PEEL ? 2 : 0); t < nt; t += 2) {
;             const bool last = (t == nt - 2);
;             const char* a1 = cA + (size_t)(t + 1) * kstepA;
;             const char* a2 = last ? nA : cA + (size_t)(t + 2) * kstepA; const char* b2 = last ? nB : cB + (size_t)(t + 2) * kstepB;
;             const char* a3 = a2 + kstepA; const char* b3 = b2 + kstepB;
;             PG8_ITER(8);
;         }
	s_setprio 0
	s_add_i32 s2, s18, s96
	v_lshl_add_u64 v[178:179], v[178:179], 0, s[36:37]
	s_mov_b32 m0, s2
	ds_read_b128 v[174:177], v188 offset:49152
	ds_read_b128 v[180:183], v188 offset:50176
	ds_read_b128 v[184:187], v188 offset:51200
	ds_read_b128 v[190:193], v188 offset:52224
	ds_read_b128 v[194:197], v188 offset:53248
	ds_read_b128 v[198:201], v188 offset:54272
	ds_read_b128 v[202:205], v188 offset:55296
	ds_read_b128 v[206:209], v188 offset:56320
	global_load_lds_dwordx4 v[178:179], off
	v_lshl_add_u64 v[178:179], v[210:211], 0, s[36:37]
	s_add_i32 m0, s2, 0x2000
	s_add_i32 s2, s38, s96
	global_load_lds_dwordx4 v[178:179], off
	v_lshl_add_u64 v[178:179], v[212:213], 0, s[36:37]
	s_mov_b32 m0, s2
	s_nop 0
	global_load_lds_dwordx4 v[178:179], off
	v_lshl_add_u64 v[178:179], v[214:215], 0, s[36:37]
	s_add_i32 m0, s2, 0x2000
	s_nop 0
	global_load_lds_dwordx4 v[178:179], off
	v_lshl_add_u64 v[178:179], s[44:45], 0, v[164:165]
	s_mov_b32 m0, s6
	s_nop 0
	global_load_lds_dwordx4 v[178:179], off
	v_lshl_add_u64 v[178:179], s[44:45], 0, v[160:161]
	s_mov_b32 m0, s56
	s_nop 0
	global_load_lds_dwordx4 v[178:179], off
	s_waitcnt vmcnt(8)
	s_waitcnt lgkmcnt(0)
	s_setprio 1
	s_barrier
	v_mfma_f32_16x16x32_bf16 v[60:63], v[122:125], v[174:177], v[60:63]
	v_mfma_f32_16x16x32_bf16 v[56:59], v[138:141], v[174:177], v[56:59]
	v_mfma_f32_16x16x32_bf16 v[44:47], v[122:125], v[184:187], v[44:47]
	v_mfma_f32_16x16x32_bf16 v[40:43], v[138:141], v[184:187], v[40:43]
	v_mfma_f32_16x16x32_bf16 v[28:31], v[122:125], v[194:197], v[28:31]
	v_mfma_f32_16x16x32_bf16 v[24:27], v[138:141], v[194:197], v[24:27]
	v_mfma_f32_16x16x32_bf16 v[12:15], v[122:125], v[202:205], v[12:15]
	v_mfma_f32_16x16x32_bf16 v[8:11], v[138:141], v[202:205], v[8:11]
	v_mfma_f32_16x16x32_bf16 v[60:63], v[126:129], v[180:183], v[60:63]
	v_mfma_f32_16x16x32_bf16 v[56:59], v[142:145], v[180:183], v[56:59]
	v_mfma_f32_16x16x32_bf16 v[44:47], v[126:129], v[190:193], v[44:47]
	v_mfma_f32_16x16x32_bf16 v[40:43], v[142:145], v[190:193], v[40:43]
	v_mfma_f32_16x16x32_bf16 v[28:31], v[126:129], v[198:201], v[28:31]
	v_mfma_f32_16x16x32_bf16 v[24:27], v[142:145], v[198:201], v[24:27]
	v_mfma_f32_16x16x32_bf16 v[12:15], v[126:129], v[206:209], v[12:15]
	v_mfma_f32_16x16x32_bf16 v[8:11], v[142:145], v[206:209], v[8:11]
	s_setprio 0
	s_setprio 1
	v_mfma_f32_16x16x32_bf16 v[52:55], v[146:149], v[174:177], v[52:55]
	v_mfma_f32_16x16x32_bf16 v[48:51], v[154:157], v[174:177], v[48:51]
	v_mfma_f32_16x16x32_bf16 v[36:39], v[146:149], v[184:187], v[36:39]
	v_mfma_f32_16x16x32_bf16 v[32:35], v[154:157], v[184:187], v[32:35]
	v_mfma_f32_16x16x32_bf16 v[20:23], v[146:149], v[194:197], v[20:23]
	v_mfma_f32_16x16x32_bf16 v[16:19], v[154:157], v[194:197], v[16:19]
	v_mfma_f32_16x16x32_bf16 v[4:7], v[146:149], v[202:205], v[4:7]
	v_mfma_f32_16x16x32_bf16 v[0:3], v[154:157], v[202:205], v[0:3]
	v_mfma_f32_16x16x32_bf16 v[52:55], v[150:153], v[180:183], v[52:55]
	v_mfma_f32_16x16x32_bf16 v[48:51], v[170:173], v[180:183], v[48:51]
	v_mfma_f32_16x16x32_bf16 v[36:39], v[150:153], v[190:193], v[36:39]
	v_mfma_f32_16x16x32_bf16 v[32:35], v[170:173], v[190:193], v[32:35]
	v_mfma_f32_16x16x32_bf16 v[20:23], v[150:153], v[198:201], v[20:23]
	v_mfma_f32_16x16x32_bf16 v[16:19], v[170:173], v[198:201], v[16:19]
	v_mfma_f32_16x16x32_bf16 v[4:7], v[150:153], v[206:209], v[4:7]
	v_mfma_f32_16x16x32_bf16 v[0:3], v[170:173], v[206:209], v[0:3]
	s_barrier
	s_setprio 0
	s_add_u32 s58, s58, 0x100
	s_addc_u32 s59, s59, 0
	s_add_u32 s24, s24, s49
	s_addc_u32 s25, s25, 0
	s_cmp_ge_u32 s10, s8
	s_cbranch_scc1 .LBB0_348

; template <class Epi, class Sched, bool ALIGN_EPI = false, bool SP2 = false>
; __device__ __forceinline__ void gemm_phase(PG8_LAS unsigned char* lds, const Gemm g, const Sched& S, const Epi& E) {
;     ...
;         const bool has_next = S.next(ui + 1, nxt);
;         const char* nA = has_next ? (const char*)g.A + (size_t)nxt.pm * tstepA : cA; const char* nB = has_next ? (const char*)g.Bt + (size_t)nxt.pn * tstepB : cB;
.LBB0_477:
	s_ashr_i32 s27, s26, 31
	s_lshl_b64 s[2:3], s[26:27], 15
	v_readlane_b32 s10, v255, 15
	s_add_u32 s28, s10, s2
	v_readlane_b32 s2, v255, 16
	s_addc_u32 s29, s2, s3
	s_ashr_i32 s25, s24, 31
	s_lshl_b64 s[2:3], s[24:25], 19
	s_add_u32 s30, s19, s2
	s_addc_u32 s31, s22, s3
	s_add_u32 s44, s34, 0x800000
	s_addc_u32 s45, s35, 0
	s_add_u32 s42, s34, 0xc00000
	s_addc_u32 s43, s35, 0
	s_add_i32 s61, 0, 0x10000
	s_and_b64 s[2:3], s[40:41], exec
	s_cselect_b32 s25, s29, s35
	s_cselect_b32 s27, s28, s34
	s_add_i32 s97, 0, 0x14000
	v_add_u32_e32 v142, s61, v97
	v_add_u32_e32 v143, s97, v97
	ds_read_b128 v[0:3], v142
	ds_read_b128 v[4:7], v142 offset:1024
	ds_read_b128 v[8:11], v142 offset:2048
	ds_read_b128 v[12:15], v142 offset:3072
	ds_read_b128 v[16:19], v143
	s_waitcnt lgkmcnt(0)
	ds_read_b128 v[20:23], v143 offset:1024
	ds_read_b128 v[24:27], v143 offset:2048
	ds_read_b128 v[28:31], v143 offset:3072
	s_and_b64 s[2:3], s[40:41], exec
	s_cselect_b32 s57, s31, s1
	s_cselect_b32 s58, s30, s0
	s_add_u32 s2, s34, 0x404000
	s_addc_u32 s3, s35, 0
	s_add_i32 s59, s23, 0xc000
	v_lshl_add_u64 v[64:65], s[2:3], 0, v[130:131]
	s_mov_b32 m0, s59
	s_add_i32 s60, s23, 0xe000
	ds_read_b128 v[32:35], v156
	ds_read_b128 v[36:39], v156 offset:1024
	ds_read_b128 v[40:43], v156 offset:2048
	ds_read_b128 v[44:47], v156 offset:3072
	ds_read_b128 v[48:51], v156 offset:4096
	ds_read_b128 v[52:55], v156 offset:5120
	ds_read_b128 v[56:59], v156 offset:6144
	ds_read_b128 v[60:63], v156 offset:7168
	global_load_lds_dwordx4 v[64:65], off
	v_lshl_add_u64 v[64:65], s[2:3], 0, v[134:135]
	s_mov_b32 m0, s60
	s_nop 0
	global_load_lds_dwordx4 v[64:65], off
	s_waitcnt vmcnt(8)
	s_waitcnt lgkmcnt(0)
	s_setprio 1
	s_barrier
	v_mfma_f32_16x16x32_bf16 v[88:91], v[0:3], v[56:59], 0
	v_mfma_f32_16x16x32_bf16 v[64:67], v[0:3], v[32:35], 0
	v_mfma_f32_16x16x32_bf16 v[68:71], v[8:11], v[32:35], 0
	v_mfma_f32_16x16x32_bf16 v[72:75], v[0:3], v[40:43], 0
	v_mfma_f32_16x16x32_bf16 v[76:79], v[8:11], v[40:43], 0
	v_mfma_f32_16x16x32_bf16 v[80:83], v[0:3], v[48:51], 0
	v_mfma_f32_16x16x32_bf16 v[84:87], v[8:11], v[48:51], 0
	v_mfma_f32_16x16x32_bf16 v[92:95], v[4:7], v[60:63], v[88:91]
	v_mfma_f32_16x16x32_bf16 v[88:91], v[8:11], v[56:59], 0
	v_mfma_f32_16x16x32_bf16 v[64:67], v[4:7], v[36:39], v[64:67]
	v_mfma_f32_16x16x32_bf16 v[68:71], v[12:15], v[36:39], v[68:71]
	v_mfma_f32_16x16x32_bf16 v[72:75], v[4:7], v[44:47], v[72:75]
	v_mfma_f32_16x16x32_bf16 v[76:79], v[12:15], v[44:47], v[76:79]
	v_mfma_f32_16x16x32_bf16 v[80:83], v[4:7], v[52:55], v[80:83]
	v_mfma_f32_16x16x32_bf16 v[84:87], v[12:15], v[52:55], v[84:87]
	v_mfma_f32_16x16x32_bf16 v[102:105], v[12:15], v[60:63], v[88:91]
	s_setprio 0
	s_setprio 1
	v_mfma_f32_16x16x32_bf16 v[88:91], v[16:19], v[32:35], 0
	v_mfma_f32_16x16x32_bf16 v[32:35], v[24:27], v[32:35], 0
	v_mfma_f32_16x16x32_bf16 v[110:113], v[20:23], v[36:39], v[88:91]
	v_mfma_f32_16x16x32_bf16 v[32:35], v[28:31], v[36:39], v[32:35]
	v_mfma_f32_16x16x32_bf16 v[36:39], v[16:19], v[40:43], 0
	v_mfma_f32_16x16x32_bf16 v[40:43], v[24:27], v[40:43], 0
	v_mfma_f32_16x16x32_bf16 v[36:39], v[20:23], v[44:47], v[36:39]
	v_mfma_f32_16x16x32_bf16 v[40:43], v[28:31], v[44:47], v[40:43]
	v_mfma_f32_16x16x32_bf16 v[44:47], v[16:19], v[48:51], 0
	v_mfma_f32_16x16x32_bf16 v[48:51], v[24:27], v[48:51], 0
	v_mfma_f32_16x16x32_bf16 v[44:47], v[20:23], v[52:55], v[44:47]
	v_mfma_f32_16x16x32_bf16 v[48:51], v[28:31], v[52:55], v[48:51]
	v_mfma_f32_16x16x32_bf16 v[52:55], v[16:19], v[56:59], 0
	v_mfma_f32_16x16x32_bf16 v[56:59], v[24:27], v[56:59], 0
	v_mfma_f32_16x16x32_bf16 v[52:55], v[20:23], v[60:63], v[52:55]
	v_mfma_f32_16x16x32_bf16 v[56:59], v[28:31], v[60:63], v[56:59]
	s_barrier
	s_setprio 0
	v_lshl_add_u64 v[154:155], s[0:1], 0, v[132:133]
	s_mov_b64 s[2:3], 0x100
	s_add_i32 s61, s61, s9
	v_lshl_add_u64 v[144:145], v[154:155], 0, s[2:3]
	s_mov_b32 m0, s61
	v_lshl_add_u64 v[178:179], s[0:1], 0, v[136:137]
	s_add_i32 s96, s61, 0x2000
	ds_read_b128 v[60:63], v156 offset:16384
	ds_read_b128 v[88:91], v156 offset:17408
	ds_read_b128 v[98:101], v156 offset:18432
	ds_read_b128 v[106:109], v156 offset:19456
	ds_read_b128 v[114:117], v156 offset:20480
	ds_read_b128 v[118:121], v156 offset:21504
	ds_read_b128 v[122:125], v156 offset:22528
	ds_read_b128 v[126:129], v156 offset:23552
	global_load_lds_dwordx4 v[144:145], off
	v_lshl_add_u64 v[144:145], v[178:179], 0, s[2:3]
	s_add_u32 s2, s0, 0x40100
	s_mov_b32 m0, s96
	s_addc_u32 s3, s1, 0
	s_add_i32 s97, s97, s9
	global_load_lds_dwordx4 v[144:145], off
	v_lshl_add_u64 v[144:145], s[2:3], 0, v[132:133]
	s_mov_b32 m0, s97
	s_add_i32 s98, s97, 0x2000
	global_load_lds_dwordx4 v[144:145], off
	v_lshl_add_u64 v[144:145], s[2:3], 0, v[136:137]
	s_mov_b32 m0, s98
	s_nop 0
	global_load_lds_dwordx4 v[144:145], off
	v_lshl_add_u64 v[144:145], s[44:45], 0, v[130:131]
	s_mov_b32 m0, s23
	s_nop 0
	global_load_lds_dwordx4 v[144:145], off
	v_lshl_add_u64 v[144:145], s[44:45], 0, v[134:135]
	s_mov_b32 m0, s39
	s_nop 0
	global_load_lds_dwordx4 v[144:145], off
	s_waitcnt vmcnt(8)
	s_waitcnt lgkmcnt(0)
	s_setprio 1
	s_barrier
	v_mfma_f32_16x16x32_bf16 v[144:147], v[0:3], v[60:63], 0
	v_mfma_f32_16x16x32_bf16 v[158:161], v[0:3], v[98:101], 0
	v_mfma_f32_16x16x32_bf16 v[166:169], v[0:3], v[114:117], 0
	v_mfma_f32_16x16x32_bf16 v[0:3], v[0:3], v[122:125], 0
	v_mfma_f32_16x16x32_bf16 v[146:149], v[4:7], v[88:91], v[144:147]
	v_mfma_f32_16x16x32_bf16 v[158:161], v[4:7], v[106:109], v[158:161]
	v_mfma_f32_16x16x32_bf16 v[166:169], v[4:7], v[118:121], v[166:169]
	v_mfma_f32_16x16x32_bf16 v[0:3], v[4:7], v[126:129], v[0:3]
	v_mfma_f32_16x16x32_bf16 v[4:7], v[8:11], v[122:125], 0
	v_mfma_f32_16x16x32_bf16 v[150:153], v[8:11], v[60:63], 0
	v_mfma_f32_16x16x32_bf16 v[162:165], v[8:11], v[98:101], 0
	v_mfma_f32_16x16x32_bf16 v[170:173], v[8:11], v[114:117], 0
	v_mfma_f32_16x16x32_bf16 v[4:7], v[12:15], v[126:129], v[4:7]
	v_mfma_f32_16x16x32_bf16 v[150:153], v[12:15], v[88:91], v[150:153]
	v_mfma_f32_16x16x32_bf16 v[162:165], v[12:15], v[106:109], v[162:165]
	v_mfma_f32_16x16x32_bf16 v[170:173], v[12:15], v[118:121], v[170:173]
	s_setprio 0
	s_setprio 1
	v_mfma_f32_16x16x32_bf16 v[8:11], v[16:19], v[60:63], 0
	v_mfma_f32_16x16x32_bf16 v[12:15], v[20:23], v[88:91], v[8:11]
	v_mfma_f32_16x16x32_bf16 v[8:11], v[24:27], v[60:63], 0
	v_mfma_f32_16x16x32_bf16 v[174:177], v[28:31], v[88:91], v[8:11]
	v_mfma_f32_16x16x32_bf16 v[8:11], v[16:19], v[98:101], 0
	v_mfma_f32_16x16x32_bf16 v[188:191], v[20:23], v[106:109], v[8:11]
	v_mfma_f32_16x16x32_bf16 v[8:11], v[24:27], v[98:101], 0
	v_mfma_f32_16x16x32_bf16 v[192:195], v[28:31], v[106:109], v[8:11]
	v_mfma_f32_16x16x32_bf16 v[8:11], v[16:19], v[114:117], 0
	v_mfma_f32_16x16x32_bf16 v[196:199], v[20:23], v[118:121], v[8:11]
	v_mfma_f32_16x16x32_bf16 v[8:11], v[24:27], v[114:117], 0
	v_mfma_f32_16x16x32_bf16 v[200:203], v[28:31], v[118:121], v[8:11]
	v_mfma_f32_16x16x32_bf16 v[8:11], v[16:19], v[122:125], 0
	v_mfma_f32_16x16x32_bf16 v[204:207], v[20:23], v[126:129], v[8:11]
	v_mfma_f32_16x16x32_bf16 v[8:11], v[24:27], v[122:125], 0
	v_mfma_f32_16x16x32_bf16 v[208:211], v[28:31], v[126:129], v[8:11]
	s_barrier
	s_setprio 0
	s_add_i32 s99, 0, 0x18000
	s_add_i32 vcc_hi, 0, 0x1c000
	v_add_u32_e32 v144, s99, v97
	v_add_u32_e32 v145, vcc_hi, v97
	s_nop 0
	ds_read_b128 v[8:11], v144
	ds_read_b128 v[20:23], v144 offset:1024
	ds_read_b128 v[28:31], v144 offset:2048
	ds_read_b128 v[212:215], v144 offset:3072
	ds_read_b128 v[216:219], v145
	ds_read_b128 v[220:223], v145 offset:1024
	ds_read_b128 v[234:237], v145 offset:2048
	ds_read_b128 v[238:241], v145 offset:3072
	s_add_u32 s2, s34, 0x804000
	s_addc_u32 s3, s35, 0
	s_mov_b32 m0, s46
	v_lshl_add_u64 v[60:61], s[2:3], 0, v[130:131]
	ds_read_b128 v[16:19], v156 offset:32768
	ds_read_b128 v[24:27], v156 offset:33792
	ds_read_b128 v[242:245], v156 offset:34816
	ds_read_b128 v[246:249], v156 offset:35840
	ds_read_b128 v[228:231], v156 offset:36864
	ds_read_b128 v[180:183], v156 offset:37888
	ds_read_b128 v[184:187], v156 offset:38912
	ds_read_b128 v[224:227], v156 offset:39936
	global_load_lds_dwordx4 v[60:61], off
	v_lshl_add_u64 v[60:61], s[2:3], 0, v[134:135]
	s_mov_b32 m0, s47
	s_nop 0
	global_load_lds_dwordx4 v[60:61], off
	s_waitcnt vmcnt(8)
	s_waitcnt lgkmcnt(0)
	s_setprio 1
	s_barrier
	v_mfma_f32_16x16x32_bf16 v[60:63], v[8:11], v[16:19], v[64:67]
	v_mfma_f32_16x16x32_bf16 v[122:125], v[20:23], v[24:27], v[60:63]
	v_mfma_f32_16x16x32_bf16 v[60:63], v[28:31], v[16:19], v[68:71]
	v_mfma_f32_16x16x32_bf16 v[114:117], v[212:215], v[24:27], v[60:63]
	v_mfma_f32_16x16x32_bf16 v[60:63], v[8:11], v[242:245], v[72:75]
	v_mfma_f32_16x16x32_bf16 v[106:109], v[20:23], v[246:249], v[60:63]
	v_mfma_f32_16x16x32_bf16 v[60:63], v[28:31], v[242:245], v[76:79]
	v_mfma_f32_16x16x32_bf16 v[98:101], v[212:215], v[246:249], v[60:63]
	v_mfma_f32_16x16x32_bf16 v[60:63], v[8:11], v[228:231], v[80:83]
	v_mfma_f32_16x16x32_bf16 v[88:91], v[20:23], v[180:183], v[60:63]
	v_mfma_f32_16x16x32_bf16 v[60:63], v[28:31], v[228:231], v[84:87]
	v_mfma_f32_16x16x32_bf16 v[80:83], v[212:215], v[180:183], v[60:63]
	v_mfma_f32_16x16x32_bf16 v[60:63], v[8:11], v[184:187], v[92:95]
	v_mfma_f32_16x16x32_bf16 v[72:75], v[20:23], v[224:227], v[60:63]
	v_mfma_f32_16x16x32_bf16 v[60:63], v[28:31], v[184:187], v[102:105]
	v_mfma_f32_16x16x32_bf16 v[60:63], v[212:215], v[224:227], v[60:63]
	s_setprio 0
	s_setprio 1
	v_mfma_f32_16x16x32_bf16 v[64:67], v[216:219], v[16:19], v[110:113]
	v_mfma_f32_16x16x32_bf16 v[16:19], v[234:237], v[16:19], v[32:35]
	v_mfma_f32_16x16x32_bf16 v[118:121], v[238:241], v[24:27], v[16:19]
	v_mfma_f32_16x16x32_bf16 v[16:19], v[216:219], v[242:245], v[36:39]
	v_mfma_f32_16x16x32_bf16 v[110:113], v[220:223], v[246:249], v[16:19]
	v_mfma_f32_16x16x32_bf16 v[16:19], v[234:237], v[242:245], v[40:43]
	v_mfma_f32_16x16x32_bf16 v[102:105], v[238:241], v[246:249], v[16:19]
	v_mfma_f32_16x16x32_bf16 v[16:19], v[216:219], v[228:231], v[44:47]
	v_mfma_f32_16x16x32_bf16 v[92:95], v[220:223], v[180:183], v[16:19]
	v_mfma_f32_16x16x32_bf16 v[16:19], v[234:237], v[228:231], v[48:51]
	v_mfma_f32_16x16x32_bf16 v[84:87], v[238:241], v[180:183], v[16:19]
	v_mfma_f32_16x16x32_bf16 v[16:19], v[216:219], v[184:187], v[52:55]
	v_mfma_f32_16x16x32_bf16 v[76:79], v[220:223], v[224:227], v[16:19]
	v_mfma_f32_16x16x32_bf16 v[16:19], v[234:237], v[184:187], v[56:59]
	v_mfma_f32_16x16x32_bf16 v[126:129], v[220:223], v[24:27], v[64:67]
	v_mfma_f32_16x16x32_bf16 v[68:71], v[238:241], v[224:227], v[16:19]
	s_barrier
; template <class Epi, class Sched, bool ALIGN_EPI = false, bool SP2 = false>
; __device__ __forceinline__ void gemm_phase(PG8_LAS unsigned char* lds, const Gemm g, const Sched& S, const Epi& E) {
;     ...
;         if constexpr (Epi::PEEL) {
;             const char* a1 = cA + kstepA; const char* a2 = cA + 2 * kstepA; const char* b2 = cB + 2 * kstepB; const char* a3 = a2 + kstepA; const char* b3 = b2 + kstepB;
;             PG8_ITER(8);
;         }
;         for (int t = (Epi::PEEL ? 2 : 0); t < nt; t += 2) {
;             const bool last = (t == nt - 2);
;             const char* a1 = cA + (size_t)(t + 1) * kstepA;
;             const char* a2 = last ? nA : cA + (size_t)(t + 2) * kstepA; const char* b2 = last ? nB : cB + (size_t)(t + 2) * kstepB;
;             const char* a3 = a2 + kstepA; const char* b3 = b2 + kstepB;
;             PG8_ITER(8);
	s_setprio 0
	s_mov_b64 s[2:3], 0x180
	s_add_i32 s99, s99, s9
	s_nop 1
	v_lshl_add_u64 v[16:17], v[154:155], 0, s[2:3]
	s_mov_b32 m0, s99
	s_add_i32 vcc_lo, s99, 0x2000
	ds_read_b128 v[36:39], v156 offset:49152
	ds_read_b128 v[44:47], v156 offset:50176
	ds_read_b128 v[180:183], v156 offset:51200
	ds_read_b128 v[184:187], v156 offset:52224
	ds_read_b128 v[224:227], v156 offset:53248
	ds_read_b128 v[228:231], v156 offset:54272
	ds_read_b128 v[242:245], v156 offset:55296
	ds_read_b128 v[246:249], v156 offset:56320
	global_load_lds_dwordx4 v[16:17], off
	v_lshl_add_u64 v[16:17], v[178:179], 0, s[2:3]
	s_add_u32 s2, s0, 0x40180
	s_mov_b32 m0, vcc_lo
	s_addc_u32 s3, s1, 0
	s_add_i32 vcc_hi, vcc_hi, s9
	global_load_lds_dwordx4 v[16:17], off
	v_lshl_add_u64 v[16:17], s[2:3], 0, v[132:133]
	s_mov_b32 m0, vcc_hi
	s_add_i32 s38, vcc_hi, 0x2000
	global_load_lds_dwordx4 v[16:17], off
	v_lshl_add_u64 v[16:17], s[2:3], 0, v[136:137]
	s_mov_b32 m0, s38
	s_nop 0
	global_load_lds_dwordx4 v[16:17], off
	v_lshl_add_u64 v[16:17], s[42:43], 0, v[130:131]
	s_mov_b32 m0, s49
	s_nop 0
	global_load_lds_dwordx4 v[16:17], off
	v_lshl_add_u64 v[16:17], s[42:43], 0, v[134:135]
	s_mov_b32 m0, s50
	s_nop 0
	global_load_lds_dwordx4 v[16:17], off
	s_waitcnt vmcnt(8)
	s_waitcnt lgkmcnt(0)
	s_setprio 1
	s_barrier
	v_mfma_f32_16x16x32_bf16 v[16:19], v[8:11], v[36:39], v[146:149]
	v_mfma_f32_16x16x32_bf16 v[56:59], v[20:23], v[44:47], v[16:19]
	v_mfma_f32_16x16x32_bf16 v[16:19], v[28:31], v[36:39], v[150:153]
	v_mfma_f32_16x16x32_bf16 v[48:51], v[212:215], v[44:47], v[16:19]
	v_mfma_f32_16x16x32_bf16 v[16:19], v[8:11], v[180:183], v[158:161]
	v_mfma_f32_16x16x32_bf16 v[40:43], v[20:23], v[184:187], v[16:19]
	v_mfma_f32_16x16x32_bf16 v[16:19], v[28:31], v[180:183], v[162:165]
	v_mfma_f32_16x16x32_bf16 v[32:35], v[212:215], v[184:187], v[16:19]
	v_mfma_f32_16x16x32_bf16 v[16:19], v[8:11], v[224:227], v[166:169]
	v_mfma_f32_16x16x32_bf16 v[0:3], v[8:11], v[242:245], v[0:3]
	v_mfma_f32_16x16x32_bf16 v[24:27], v[20:23], v[228:231], v[16:19]
	v_mfma_f32_16x16x32_bf16 v[16:19], v[28:31], v[224:227], v[170:173]
	v_mfma_f32_16x16x32_bf16 v[8:11], v[20:23], v[246:249], v[0:3]
	v_mfma_f32_16x16x32_bf16 v[0:3], v[28:31], v[242:245], v[4:7]
	v_mfma_f32_16x16x32_bf16 v[16:19], v[212:215], v[228:231], v[16:19]
	v_mfma_f32_16x16x32_bf16 v[0:3], v[212:215], v[246:249], v[0:3]
	s_setprio 0
	s_setprio 1
	v_mfma_f32_16x16x32_bf16 v[4:7], v[216:219], v[36:39], v[12:15]
	v_mfma_f32_16x16x32_bf16 v[64:67], v[220:223], v[44:47], v[4:7]
	v_mfma_f32_16x16x32_bf16 v[4:7], v[234:237], v[36:39], v[174:177]
	v_mfma_f32_16x16x32_bf16 v[52:55], v[238:241], v[44:47], v[4:7]
	v_mfma_f32_16x16x32_bf16 v[4:7], v[216:219], v[180:183], v[188:191]
	v_mfma_f32_16x16x32_bf16 v[44:47], v[220:223], v[184:187], v[4:7]
	v_mfma_f32_16x16x32_bf16 v[4:7], v[234:237], v[180:183], v[192:195]
	v_mfma_f32_16x16x32_bf16 v[36:39], v[238:241], v[184:187], v[4:7]
	v_mfma_f32_16x16x32_bf16 v[4:7], v[216:219], v[224:227], v[196:199]
	v_mfma_f32_16x16x32_bf16 v[28:31], v[220:223], v[228:231], v[4:7]
	v_mfma_f32_16x16x32_bf16 v[4:7], v[234:237], v[224:227], v[200:203]
	v_mfma_f32_16x16x32_bf16 v[20:23], v[238:241], v[228:231], v[4:7]
	v_mfma_f32_16x16x32_bf16 v[4:7], v[216:219], v[242:245], v[204:207]
	v_mfma_f32_16x16x32_bf16 v[12:15], v[220:223], v[246:249], v[4:7]
	v_mfma_f32_16x16x32_bf16 v[4:7], v[234:237], v[242:245], v[208:211]
	v_mfma_f32_16x16x32_bf16 v[4:7], v[238:241], v[246:249], v[4:7]
	s_barrier
	s_setprio 0
	s_add_u32 s3, s0, 0x200
	s_addc_u32 s2, s1, 0
	s_add_u32 s0, s34, 0xc04000
	s_addc_u32 s1, s35, 0
	s_mov_b32 s18, 0
.LBB0_478:
	ds_read_b128 v[146:149], v142
	ds_read_b128 v[150:153], v142 offset:1024
	ds_read_b128 v[158:161], v142 offset:2048
	ds_read_b128 v[162:165], v142 offset:3072
	ds_read_b128 v[166:169], v143
	ds_read_b128 v[170:173], v143 offset:1024
	ds_read_b128 v[174:177], v143 offset:2048
	ds_read_b128 v[180:183], v143 offset:3072
	s_add_u32 s10, s0, 0x3fc000
	s_addc_u32 s11, s1, 0
	s_cmp_eq_u32 s18, 12
	s_cselect_b32 s44, s27, s10
	s_cselect_b32 s45, s25, s11
	s_cselect_b32 s42, s58, s3
	s_cselect_b32 s43, s57, s2
	s_add_u32 s34, s44, 0x400000
	s_addc_u32 s35, s45, 0
	s_mov_b32 m0, s59
	v_lshl_add_u64 v[154:155], s[0:1], 0, v[140:141]
	ds_read_b128 v[184:187], v156
	ds_read_b128 v[188:191], v156 offset:1024
	ds_read_b128 v[192:195], v156 offset:2048
	ds_read_b128 v[196:199], v156 offset:3072
	ds_read_b128 v[200:203], v156 offset:4096
	ds_read_b128 v[204:207], v156 offset:5120
	ds_read_b128 v[208:211], v156 offset:6144
	ds_read_b128 v[212:215], v156 offset:7168
	global_load_lds_dwordx4 v[154:155], off
	v_lshl_add_u64 v[154:155], s[0:1], 0, v[138:139]
	s_mov_b32 m0, s60
	s_nop 0
	global_load_lds_dwordx4 v[154:155], off
	s_waitcnt vmcnt(8)
	s_waitcnt lgkmcnt(0)
	s_setprio 1
	s_barrier
	v_mfma_f32_16x16x32_bf16 v[122:125], v[146:149], v[184:187], v[122:125]
	v_mfma_f32_16x16x32_bf16 v[114:117], v[158:161], v[184:187], v[114:117]
	v_mfma_f32_16x16x32_bf16 v[106:109], v[146:149], v[192:195], v[106:109]
	v_mfma_f32_16x16x32_bf16 v[98:101], v[158:161], v[192:195], v[98:101]
	v_mfma_f32_16x16x32_bf16 v[88:91], v[146:149], v[200:203], v[88:91]
	v_mfma_f32_16x16x32_bf16 v[80:83], v[158:161], v[200:203], v[80:83]
	v_mfma_f32_16x16x32_bf16 v[72:75], v[146:149], v[208:211], v[72:75]
	v_mfma_f32_16x16x32_bf16 v[60:63], v[158:161], v[208:211], v[60:63]
	v_mfma_f32_16x16x32_bf16 v[122:125], v[150:153], v[188:191], v[122:125]
	v_mfma_f32_16x16x32_bf16 v[114:117], v[162:165], v[188:191], v[114:117]
	v_mfma_f32_16x16x32_bf16 v[106:109], v[150:153], v[196:199], v[106:109]
	v_mfma_f32_16x16x32_bf16 v[98:101], v[162:165], v[196:199], v[98:101]
	v_mfma_f32_16x16x32_bf16 v[88:91], v[150:153], v[204:207], v[88:91]
	v_mfma_f32_16x16x32_bf16 v[80:83], v[162:165], v[204:207], v[80:83]
	v_mfma_f32_16x16x32_bf16 v[72:75], v[150:153], v[212:215], v[72:75]
	v_mfma_f32_16x16x32_bf16 v[60:63], v[162:165], v[212:215], v[60:63]
	s_setprio 0
	s_setprio 1
	v_mfma_f32_16x16x32_bf16 v[126:129], v[166:169], v[184:187], v[126:129]
	v_mfma_f32_16x16x32_bf16 v[118:121], v[174:177], v[184:187], v[118:121]
	v_mfma_f32_16x16x32_bf16 v[110:113], v[166:169], v[192:195], v[110:113]
	v_mfma_f32_16x16x32_bf16 v[102:105], v[174:177], v[192:195], v[102:105]
	v_mfma_f32_16x16x32_bf16 v[92:95], v[166:169], v[200:203], v[92:95]
	v_mfma_f32_16x16x32_bf16 v[84:87], v[174:177], v[200:203], v[84:87]
	v_mfma_f32_16x16x32_bf16 v[76:79], v[166:169], v[208:211], v[76:79]
	v_mfma_f32_16x16x32_bf16 v[68:71], v[174:177], v[208:211], v[68:71]
	v_mfma_f32_16x16x32_bf16 v[126:129], v[170:173], v[188:191], v[126:129]
	v_mfma_f32_16x16x32_bf16 v[118:121], v[180:183], v[188:191], v[118:121]
	v_mfma_f32_16x16x32_bf16 v[110:113], v[170:173], v[196:199], v[110:113]
	v_mfma_f32_16x16x32_bf16 v[102:105], v[180:183], v[196:199], v[102:105]
	v_mfma_f32_16x16x32_bf16 v[92:95], v[170:173], v[204:207], v[92:95]
	v_mfma_f32_16x16x32_bf16 v[84:87], v[180:183], v[204:207], v[84:87]
	v_mfma_f32_16x16x32_bf16 v[76:79], v[170:173], v[212:215], v[76:79]
	v_mfma_f32_16x16x32_bf16 v[68:71], v[180:183], v[212:215], v[68:71]
	s_barrier
	s_setprio 0
	s_mov_b32 m0, s61
	v_lshl_add_u64 v[154:155], s[42:43], 0, v[132:133]
	s_add_u32 s10, s42, 0x40000
	ds_read_b128 v[184:187], v156 offset:16384
	ds_read_b128 v[188:191], v156 offset:17408
	ds_read_b128 v[192:195], v156 offset:18432
	ds_read_b128 v[196:199], v156 offset:19456
	ds_read_b128 v[200:203], v156 offset:20480
	ds_read_b128 v[204:207], v156 offset:21504
	ds_read_b128 v[208:211], v156 offset:22528
	ds_read_b128 v[212:215], v156 offset:23552
	global_load_lds_dwordx4 v[154:155], off
	v_lshl_add_u64 v[178:179], s[42:43], 0, v[136:137]
	s_mov_b32 m0, s96
	s_addc_u32 s11, s43, 0
	global_load_lds_dwordx4 v[178:179], off
	v_lshl_add_u64 v[216:217], s[10:11], 0, v[132:133]
	s_mov_b32 m0, s97
	s_nop 0
	global_load_lds_dwordx4 v[216:217], off
	v_lshl_add_u64 v[216:217], s[10:11], 0, v[136:137]
	s_mov_b32 m0, s98
	s_nop 0
	global_load_lds_dwordx4 v[216:217], off
	v_lshl_add_u64 v[216:217], s[44:45], 0, v[130:131]
	s_mov_b32 m0, s23
	s_nop 0
	global_load_lds_dwordx4 v[216:217], off
	v_lshl_add_u64 v[216:217], s[44:45], 0, v[134:135]
	s_mov_b32 m0, s39
	s_nop 0
	global_load_lds_dwordx4 v[216:217], off
	s_waitcnt vmcnt(8)
	s_waitcnt lgkmcnt(0)
	s_setprio 1
	s_barrier
	v_mfma_f32_16x16x32_bf16 v[56:59], v[146:149], v[184:187], v[56:59]
	v_mfma_f32_16x16x32_bf16 v[48:51], v[158:161], v[184:187], v[48:51]
	v_mfma_f32_16x16x32_bf16 v[40:43], v[146:149], v[192:195], v[40:43]
	v_mfma_f32_16x16x32_bf16 v[32:35], v[158:161], v[192:195], v[32:35]
	v_mfma_f32_16x16x32_bf16 v[24:27], v[146:149], v[200:203], v[24:27]
	v_mfma_f32_16x16x32_bf16 v[16:19], v[158:161], v[200:203], v[16:19]
	v_mfma_f32_16x16x32_bf16 v[8:11], v[146:149], v[208:211], v[8:11]
	v_mfma_f32_16x16x32_bf16 v[0:3], v[158:161], v[208:211], v[0:3]
	v_mfma_f32_16x16x32_bf16 v[56:59], v[150:153], v[188:191], v[56:59]
	v_mfma_f32_16x16x32_bf16 v[48:51], v[162:165], v[188:191], v[48:51]
	v_mfma_f32_16x16x32_bf16 v[40:43], v[150:153], v[196:199], v[40:43]
	v_mfma_f32_16x16x32_bf16 v[32:35], v[162:165], v[196:199], v[32:35]
	v_mfma_f32_16x16x32_bf16 v[24:27], v[150:153], v[204:207], v[24:27]
	v_mfma_f32_16x16x32_bf16 v[16:19], v[162:165], v[204:207], v[16:19]
	v_mfma_f32_16x16x32_bf16 v[8:11], v[150:153], v[212:215], v[8:11]
	v_mfma_f32_16x16x32_bf16 v[0:3], v[162:165], v[212:215], v[0:3]
	s_setprio 0
	s_setprio 1
	v_mfma_f32_16x16x32_bf16 v[64:67], v[166:169], v[184:187], v[64:67]
	v_mfma_f32_16x16x32_bf16 v[52:55], v[174:177], v[184:187], v[52:55]
	v_mfma_f32_16x16x32_bf16 v[44:47], v[166:169], v[192:195], v[44:47]
	v_mfma_f32_16x16x32_bf16 v[36:39], v[174:177], v[192:195], v[36:39]
	v_mfma_f32_16x16x32_bf16 v[28:31], v[166:169], v[200:203], v[28:31]
	v_mfma_f32_16x16x32_bf16 v[20:23], v[174:177], v[200:203], v[20:23]
	v_mfma_f32_16x16x32_bf16 v[12:15], v[166:169], v[208:211], v[12:15]
	v_mfma_f32_16x16x32_bf16 v[4:7], v[174:177], v[208:211], v[4:7]
	v_mfma_f32_16x16x32_bf16 v[64:67], v[170:173], v[188:191], v[64:67]
	v_mfma_f32_16x16x32_bf16 v[52:55], v[180:183], v[188:191], v[52:55]
	v_mfma_f32_16x16x32_bf16 v[44:47], v[170:173], v[196:199], v[44:47]
	v_mfma_f32_16x16x32_bf16 v[36:39], v[180:183], v[196:199], v[36:39]
	v_mfma_f32_16x16x32_bf16 v[28:31], v[170:173], v[204:207], v[28:31]
	v_mfma_f32_16x16x32_bf16 v[20:23], v[180:183], v[204:207], v[20:23]
	v_mfma_f32_16x16x32_bf16 v[12:15], v[170:173], v[212:215], v[12:15]
	v_mfma_f32_16x16x32_bf16 v[4:7], v[180:183], v[212:215], v[4:7]
	s_barrier
; #define PG8_BAR __builtin_amdgcn_s_barrier()
; template <class Epi, class Sched, bool ALIGN_EPI = false, bool SP2 = false>
; __device__ __forceinline__ void gemm_phase(PG8_LAS unsigned char* lds, const Gemm g, const Sched& S, const Epi& E) {
;     ...
;         if constexpr (Epi::PEEL) {
;             const char* a1 = cA + kstepA; const char* a2 = cA + 2 * kstepA; const char* b2 = cB + 2 * kstepB; const char* a3 = a2 + kstepA; const char* b3 = b2 + kstepB;
;             PG8_ITER(8);
;         }
;         for (int t = (Epi::PEEL ? 2 : 0); t < nt; t += 2) {
;             const bool last = (t == nt - 2);
;             const char* a1 = cA + (size_t)(t + 1) * kstepA;
;             const char* a2 = last ? nA : cA + (size_t)(t + 2) * kstepA; const char* b2 = last ? nB : cB + (size_t)(t + 2) * kstepB;
;             const char* a3 = a2 + kstepA; const char* b3 = b2 + kstepB;
;             PG8_ITER(8);
;         }
;     ...
;         if constexpr (ALIGN_EPI) { if (wr == 0) PG8_BAR; }
	s_setprio 0
	ds_read_b128 v[146:149], v144
	ds_read_b128 v[150:153], v144 offset:1024
	ds_read_b128 v[158:161], v144 offset:2048
	ds_read_b128 v[162:165], v144 offset:3072
	ds_read_b128 v[166:169], v145
	ds_read_b128 v[170:173], v145 offset:1024
	ds_read_b128 v[174:177], v145 offset:2048
	ds_read_b128 v[180:183], v145 offset:3072
	s_add_u32 s10, s44, 0x4000
	s_addc_u32 s11, s45, 0
	s_mov_b32 m0, s46
	v_lshl_add_u64 v[216:217], s[10:11], 0, v[130:131]
	ds_read_b128 v[184:187], v156 offset:32768
	ds_read_b128 v[188:191], v156 offset:33792
	ds_read_b128 v[192:195], v156 offset:34816
	ds_read_b128 v[196:199], v156 offset:35840
	ds_read_b128 v[200:203], v156 offset:36864
	ds_read_b128 v[204:207], v156 offset:37888
	ds_read_b128 v[208:211], v156 offset:38912
	ds_read_b128 v[212:215], v156 offset:39936
	global_load_lds_dwordx4 v[216:217], off
	v_lshl_add_u64 v[216:217], s[10:11], 0, v[134:135]
	s_mov_b32 m0, s47
	s_nop 0
	global_load_lds_dwordx4 v[216:217], off
	s_waitcnt vmcnt(8)
	s_waitcnt lgkmcnt(0)
	s_setprio 1
	s_barrier
	v_mfma_f32_16x16x32_bf16 v[122:125], v[146:149], v[184:187], v[122:125]
	v_mfma_f32_16x16x32_bf16 v[114:117], v[158:161], v[184:187], v[114:117]
	v_mfma_f32_16x16x32_bf16 v[106:109], v[146:149], v[192:195], v[106:109]
	v_mfma_f32_16x16x32_bf16 v[98:101], v[158:161], v[192:195], v[98:101]
	v_mfma_f32_16x16x32_bf16 v[88:91], v[146:149], v[200:203], v[88:91]
	v_mfma_f32_16x16x32_bf16 v[80:83], v[158:161], v[200:203], v[80:83]
	v_mfma_f32_16x16x32_bf16 v[72:75], v[146:149], v[208:211], v[72:75]
	v_mfma_f32_16x16x32_bf16 v[60:63], v[158:161], v[208:211], v[60:63]
	v_mfma_f32_16x16x32_bf16 v[122:125], v[150:153], v[188:191], v[122:125]
	v_mfma_f32_16x16x32_bf16 v[114:117], v[162:165], v[188:191], v[114:117]
	v_mfma_f32_16x16x32_bf16 v[106:109], v[150:153], v[196:199], v[106:109]
	v_mfma_f32_16x16x32_bf16 v[98:101], v[162:165], v[196:199], v[98:101]
	v_mfma_f32_16x16x32_bf16 v[88:91], v[150:153], v[204:207], v[88:91]
	v_mfma_f32_16x16x32_bf16 v[80:83], v[162:165], v[204:207], v[80:83]
	v_mfma_f32_16x16x32_bf16 v[72:75], v[150:153], v[212:215], v[72:75]
	v_mfma_f32_16x16x32_bf16 v[60:63], v[162:165], v[212:215], v[60:63]
	s_setprio 0
	s_setprio 1
	v_mfma_f32_16x16x32_bf16 v[126:129], v[166:169], v[184:187], v[126:129]
	v_mfma_f32_16x16x32_bf16 v[118:121], v[174:177], v[184:187], v[118:121]
	v_mfma_f32_16x16x32_bf16 v[110:113], v[166:169], v[192:195], v[110:113]
	v_mfma_f32_16x16x32_bf16 v[102:105], v[174:177], v[192:195], v[102:105]
	v_mfma_f32_16x16x32_bf16 v[92:95], v[166:169], v[200:203], v[92:95]
	v_mfma_f32_16x16x32_bf16 v[84:87], v[174:177], v[200:203], v[84:87]
	v_mfma_f32_16x16x32_bf16 v[76:79], v[166:169], v[208:211], v[76:79]
	v_mfma_f32_16x16x32_bf16 v[68:71], v[174:177], v[208:211], v[68:71]
	v_mfma_f32_16x16x32_bf16 v[126:129], v[170:173], v[188:191], v[126:129]
	v_mfma_f32_16x16x32_bf16 v[118:121], v[180:183], v[188:191], v[118:121]
	v_mfma_f32_16x16x32_bf16 v[110:113], v[170:173], v[196:199], v[110:113]
	v_mfma_f32_16x16x32_bf16 v[102:105], v[180:183], v[196:199], v[102:105]
	v_mfma_f32_16x16x32_bf16 v[92:95], v[170:173], v[204:207], v[92:95]
	v_mfma_f32_16x16x32_bf16 v[84:87], v[180:183], v[204:207], v[84:87]
	v_mfma_f32_16x16x32_bf16 v[76:79], v[170:173], v[212:215], v[76:79]
	v_mfma_f32_16x16x32_bf16 v[68:71], v[180:183], v[212:215], v[68:71]
	s_barrier
	s_setprio 0
	s_mov_b32 m0, s99
	v_lshl_add_u64 v[154:155], v[154:155], 0, s[36:37]
	s_add_u32 s10, s42, 0x40080
	ds_read_b128 v[184:187], v156 offset:49152
	ds_read_b128 v[188:191], v156 offset:50176
	ds_read_b128 v[192:195], v156 offset:51200
	ds_read_b128 v[196:199], v156 offset:52224
	ds_read_b128 v[200:203], v156 offset:53248
	ds_read_b128 v[204:207], v156 offset:54272
	ds_read_b128 v[208:211], v156 offset:55296
	ds_read_b128 v[212:215], v156 offset:56320
	global_load_lds_dwordx4 v[154:155], off
	v_lshl_add_u64 v[154:155], v[178:179], 0, s[36:37]
	s_mov_b32 m0, vcc_lo
	s_addc_u32 s11, s43, 0
	global_load_lds_dwordx4 v[154:155], off
	v_lshl_add_u64 v[154:155], s[10:11], 0, v[132:133]
	s_mov_b32 m0, vcc_hi
	s_nop 0
	global_load_lds_dwordx4 v[154:155], off
	v_lshl_add_u64 v[154:155], s[10:11], 0, v[136:137]
	s_mov_b32 m0, s38
	s_nop 0
	global_load_lds_dwordx4 v[154:155], off
	v_lshl_add_u64 v[154:155], s[34:35], 0, v[130:131]
	s_mov_b32 m0, s49
	s_nop 0
	global_load_lds_dwordx4 v[154:155], off
	v_lshl_add_u64 v[154:155], s[34:35], 0, v[134:135]
	s_mov_b32 m0, s50
	s_nop 0
	global_load_lds_dwordx4 v[154:155], off
	s_waitcnt vmcnt(8)
	s_waitcnt lgkmcnt(0)
	s_setprio 1
	s_barrier
	v_mfma_f32_16x16x32_bf16 v[56:59], v[146:149], v[184:187], v[56:59]
	v_mfma_f32_16x16x32_bf16 v[48:51], v[158:161], v[184:187], v[48:51]
	v_mfma_f32_16x16x32_bf16 v[40:43], v[146:149], v[192:195], v[40:43]
	v_mfma_f32_16x16x32_bf16 v[32:35], v[158:161], v[192:195], v[32:35]
	v_mfma_f32_16x16x32_bf16 v[24:27], v[146:149], v[200:203], v[24:27]
	v_mfma_f32_16x16x32_bf16 v[16:19], v[158:161], v[200:203], v[16:19]
	v_mfma_f32_16x16x32_bf16 v[8:11], v[146:149], v[208:211], v[8:11]
	v_mfma_f32_16x16x32_bf16 v[0:3], v[158:161], v[208:211], v[0:3]
	v_mfma_f32_16x16x32_bf16 v[56:59], v[150:153], v[188:191], v[56:59]
	v_mfma_f32_16x16x32_bf16 v[48:51], v[162:165], v[188:191], v[48:51]
	v_mfma_f32_16x16x32_bf16 v[40:43], v[150:153], v[196:199], v[40:43]
	v_mfma_f32_16x16x32_bf16 v[32:35], v[162:165], v[196:199], v[32:35]
	v_mfma_f32_16x16x32_bf16 v[24:27], v[150:153], v[204:207], v[24:27]
	v_mfma_f32_16x16x32_bf16 v[16:19], v[162:165], v[204:207], v[16:19]
	v_mfma_f32_16x16x32_bf16 v[8:11], v[150:153], v[212:215], v[8:11]
	v_mfma_f32_16x16x32_bf16 v[0:3], v[162:165], v[212:215], v[0:3]
	s_setprio 0
	s_setprio 1
	v_mfma_f32_16x16x32_bf16 v[64:67], v[166:169], v[184:187], v[64:67]
	v_mfma_f32_16x16x32_bf16 v[52:55], v[174:177], v[184:187], v[52:55]
	v_mfma_f32_16x16x32_bf16 v[44:47], v[166:169], v[192:195], v[44:47]
	v_mfma_f32_16x16x32_bf16 v[36:39], v[174:177], v[192:195], v[36:39]
	v_mfma_f32_16x16x32_bf16 v[28:31], v[166:169], v[200:203], v[28:31]
	v_mfma_f32_16x16x32_bf16 v[20:23], v[174:177], v[200:203], v[20:23]
	v_mfma_f32_16x16x32_bf16 v[12:15], v[166:169], v[208:211], v[12:15]
	v_mfma_f32_16x16x32_bf16 v[4:7], v[174:177], v[208:211], v[4:7]
	v_mfma_f32_16x16x32_bf16 v[64:67], v[170:173], v[188:191], v[64:67]
	v_mfma_f32_16x16x32_bf16 v[52:55], v[180:183], v[188:191], v[52:55]
	v_mfma_f32_16x16x32_bf16 v[44:47], v[170:173], v[196:199], v[44:47]
	v_mfma_f32_16x16x32_bf16 v[36:39], v[180:183], v[196:199], v[36:39]
	v_mfma_f32_16x16x32_bf16 v[28:31], v[170:173], v[204:207], v[28:31]
	v_mfma_f32_16x16x32_bf16 v[20:23], v[180:183], v[204:207], v[20:23]
	v_mfma_f32_16x16x32_bf16 v[12:15], v[170:173], v[212:215], v[12:15]
	v_mfma_f32_16x16x32_bf16 v[4:7], v[180:183], v[212:215], v[4:7]
	s_barrier
	s_setprio 0
	s_add_i32 s18, s18, 2
	s_add_u32 s3, s3, 0x100
	s_addc_u32 s2, s2, 0
	s_add_u32 s0, s0, 0x800000
	s_addc_u32 s1, s1, 0
	s_cmp_gt_u32 s18, 13
	s_cbranch_scc0 .LBB0_478
	s_and_b64 vcc, exec, s[16:17]
	s_cbranch_vccz .LBB0_481
	s_barrier
